# all K-loop LDS-DMA loads in saddr form; +0x80 addresses via offset:128 with M0 compensated; no 64-bit VALU address adds left in the loops
# speedup vs baseline: 1.0028x; 1.0028x over previous
.LBB0_134:
	s_add_u32 s28, s66, 0xfffc0080
	s_addc_u32 s29, s67, -1
	s_add_i32 s88, 0, 0x10000
	v_add_u32_e32 v152, s88, v191
	ds_read_b128 v[128:131], v152
	ds_read_b128 v[132:135], v152 offset:1024
	ds_read_b128 v[148:151], v152 offset:2048
	ds_read_b128 v[152:155], v152 offset:3072
	s_cmp_eq_u32 vcc_lo, 12
	s_cselect_b32 s71, s5, s29
	s_cselect_b32 s70, s7, s28
	s_cselect_b32 s69, s17, s91
	s_cselect_b32 s68, s19, s85
	s_add_i32 m0, s73, 0xc000
	ds_read_b128 v[156:159], v192
	ds_read_b128 v[164:167], v192 offset:2048
	ds_read_b128 v[194:197], v192 offset:4096
	ds_read_b128 v[202:205], v192 offset:6144
	ds_read_b128 v[160:163], v192 offset:1024
	ds_read_b128 v[168:171], v192 offset:3072
	ds_read_b128 v[198:201], v192 offset:5120
	ds_read_b128 v[206:209], v192 offset:7168
	global_load_lds_dwordx4 v144, s[66:67]
	s_add_i32 m0, s73, 0xe000
	s_nop 0
	global_load_lds_dwordx4 v146, s[66:67]
	s_waitcnt lgkmcnt(8)
	s_barrier
	s_waitcnt lgkmcnt(7)
	v_mfma_f32_16x16x32_bf16 v[124:127], v[128:131], v[156:159], v[124:127]
	v_mfma_f32_16x16x32_bf16 v[120:123], v[148:151], v[156:159], v[120:123]
	s_waitcnt lgkmcnt(6)
	v_mfma_f32_16x16x32_bf16 v[108:111], v[128:131], v[164:167], v[108:111]
	v_mfma_f32_16x16x32_bf16 v[104:107], v[148:151], v[164:167], v[104:107]
	s_waitcnt lgkmcnt(5)
	v_mfma_f32_16x16x32_bf16 v[92:95], v[128:131], v[194:197], v[92:95]
	v_mfma_f32_16x16x32_bf16 v[88:91], v[148:151], v[194:197], v[88:91]
	s_waitcnt lgkmcnt(4)
	v_mfma_f32_16x16x32_bf16 v[76:79], v[128:131], v[202:205], v[76:79]
	v_mfma_f32_16x16x32_bf16 v[72:75], v[148:151], v[202:205], v[72:75]
	s_waitcnt lgkmcnt(3)
	v_mfma_f32_16x16x32_bf16 v[124:127], v[132:135], v[160:163], v[124:127]
	v_mfma_f32_16x16x32_bf16 v[120:123], v[152:155], v[160:163], v[120:123]
	s_waitcnt lgkmcnt(2)
	v_mfma_f32_16x16x32_bf16 v[108:111], v[132:135], v[168:171], v[108:111]
	v_mfma_f32_16x16x32_bf16 v[104:107], v[152:155], v[168:171], v[104:107]
	s_waitcnt lgkmcnt(1)
	v_mfma_f32_16x16x32_bf16 v[92:95], v[132:135], v[198:201], v[92:95]
	v_mfma_f32_16x16x32_bf16 v[88:91], v[152:155], v[198:201], v[88:91]
	s_waitcnt lgkmcnt(0)
	v_mfma_f32_16x16x32_bf16 v[76:79], v[132:135], v[206:209], v[76:79]
	v_mfma_f32_16x16x32_bf16 v[72:75], v[152:155], v[206:209], v[72:75]
	s_barrier
	s_add_i32 s89, 0, 0x14000
	v_add_u32_e32 v172, s89, v191
	s_add_i32 s28, s88, s72
	ds_read_b128 v[210:213], v172
	ds_read_b128 v[214:217], v172 offset:1024
	ds_read_b128 v[232:235], v172 offset:2048
	ds_read_b128 v[236:239], v172 offset:3072
	s_mov_b32 m0, s28
	s_nop 0
	global_load_lds_dwordx4 v138, s[68:69]
	s_add_i32 m0, s28, 0x2000
	s_nop 0
	global_load_lds_dwordx4 v142, s[68:69]
	s_barrier
	s_waitcnt lgkmcnt(3)
	v_mfma_f32_16x16x32_bf16 v[116:119], v[210:213], v[156:159], v[116:119]
	s_waitcnt lgkmcnt(1)
	v_mfma_f32_16x16x32_bf16 v[112:115], v[232:235], v[156:159], v[112:115]
	v_mfma_f32_16x16x32_bf16 v[100:103], v[210:213], v[164:167], v[100:103]
	v_mfma_f32_16x16x32_bf16 v[96:99], v[232:235], v[164:167], v[96:99]
	v_mfma_f32_16x16x32_bf16 v[84:87], v[210:213], v[194:197], v[84:87]
	v_mfma_f32_16x16x32_bf16 v[80:83], v[232:235], v[194:197], v[80:83]
	v_mfma_f32_16x16x32_bf16 v[68:71], v[210:213], v[202:205], v[68:71]
	v_mfma_f32_16x16x32_bf16 v[64:67], v[232:235], v[202:205], v[64:67]
	v_mfma_f32_16x16x32_bf16 v[116:119], v[214:217], v[160:163], v[116:119]
	s_waitcnt lgkmcnt(0)
	v_mfma_f32_16x16x32_bf16 v[112:115], v[236:239], v[160:163], v[112:115]
	v_mfma_f32_16x16x32_bf16 v[100:103], v[214:217], v[168:171], v[100:103]
	v_mfma_f32_16x16x32_bf16 v[96:99], v[236:239], v[168:171], v[96:99]
	v_mfma_f32_16x16x32_bf16 v[84:87], v[214:217], v[198:201], v[84:87]
	v_mfma_f32_16x16x32_bf16 v[80:83], v[236:239], v[198:201], v[80:83]
	v_mfma_f32_16x16x32_bf16 v[68:71], v[214:217], v[206:209], v[68:71]
	v_mfma_f32_16x16x32_bf16 v[64:67], v[236:239], v[206:209], v[64:67]
	s_mov_b32 m0, s73
	s_barrier
	ds_read_b128 v[156:159], v192 offset:16384
	ds_read_b128 v[164:167], v192 offset:18432
	ds_read_b128 v[194:197], v192 offset:20480
	ds_read_b128 v[202:205], v192 offset:22528
	ds_read_b128 v[160:163], v192 offset:17408
	ds_read_b128 v[168:171], v192 offset:19456
	ds_read_b128 v[198:201], v192 offset:21504
	ds_read_b128 v[206:209], v192 offset:23552
	global_load_lds_dwordx4 v136, s[70:71]
	s_mov_b32 m0, s74
	s_nop 0
	global_load_lds_dwordx4 v140, s[70:71]
	s_barrier
	s_waitcnt lgkmcnt(7)
	v_mfma_f32_16x16x32_bf16 v[60:63], v[128:131], v[156:159], v[60:63]
	v_mfma_f32_16x16x32_bf16 v[56:59], v[148:151], v[156:159], v[56:59]
	s_waitcnt lgkmcnt(6)
	v_mfma_f32_16x16x32_bf16 v[44:47], v[128:131], v[164:167], v[44:47]
	v_mfma_f32_16x16x32_bf16 v[40:43], v[148:151], v[164:167], v[40:43]
	s_waitcnt lgkmcnt(5)
	v_mfma_f32_16x16x32_bf16 v[28:31], v[128:131], v[194:197], v[28:31]
	v_mfma_f32_16x16x32_bf16 v[24:27], v[148:151], v[194:197], v[24:27]
	s_waitcnt lgkmcnt(4)
	v_mfma_f32_16x16x32_bf16 v[12:15], v[128:131], v[202:205], v[12:15]
	v_mfma_f32_16x16x32_bf16 v[8:11], v[148:151], v[202:205], v[8:11]
	s_waitcnt lgkmcnt(3)
	v_mfma_f32_16x16x32_bf16 v[60:63], v[132:135], v[160:163], v[60:63]
	v_mfma_f32_16x16x32_bf16 v[56:59], v[152:155], v[160:163], v[56:59]
	s_waitcnt lgkmcnt(2)
	v_mfma_f32_16x16x32_bf16 v[44:47], v[132:135], v[168:171], v[44:47]
	v_mfma_f32_16x16x32_bf16 v[40:43], v[152:155], v[168:171], v[40:43]
	s_waitcnt lgkmcnt(1)
	v_mfma_f32_16x16x32_bf16 v[28:31], v[132:135], v[198:201], v[28:31]
	v_mfma_f32_16x16x32_bf16 v[24:27], v[152:155], v[198:201], v[24:27]
	s_waitcnt lgkmcnt(0)
	v_mfma_f32_16x16x32_bf16 v[12:15], v[132:135], v[206:209], v[12:15]
	v_mfma_f32_16x16x32_bf16 v[8:11], v[152:155], v[206:209], v[8:11]
	s_barrier
	s_add_u32 s28, s68, 0x40000
	s_addc_u32 s29, s69, 0
	s_add_i32 s88, s89, s72
	s_mov_b32 m0, s88
	s_nop 0
	global_load_lds_dwordx4 v138, s[28:29]
	s_add_i32 m0, s88, 0x2000
	s_nop 0
	global_load_lds_dwordx4 v142, s[28:29]
	s_waitcnt vmcnt(6)
	s_barrier
	v_mfma_f32_16x16x32_bf16 v[52:55], v[210:213], v[156:159], v[52:55]
	v_mfma_f32_16x16x32_bf16 v[48:51], v[232:235], v[156:159], v[48:51]
	v_mfma_f32_16x16x32_bf16 v[36:39], v[210:213], v[164:167], v[36:39]
	v_mfma_f32_16x16x32_bf16 v[32:35], v[232:235], v[164:167], v[32:35]
	v_mfma_f32_16x16x32_bf16 v[20:23], v[210:213], v[194:197], v[20:23]
	v_mfma_f32_16x16x32_bf16 v[16:19], v[232:235], v[194:197], v[16:19]
	v_mfma_f32_16x16x32_bf16 v[4:7], v[210:213], v[202:205], v[4:7]
	v_mfma_f32_16x16x32_bf16 v[0:3], v[232:235], v[202:205], v[0:3]
	v_mfma_f32_16x16x32_bf16 v[52:55], v[214:217], v[160:163], v[52:55]
	v_mfma_f32_16x16x32_bf16 v[48:51], v[236:239], v[160:163], v[48:51]
	v_mfma_f32_16x16x32_bf16 v[36:39], v[214:217], v[168:171], v[36:39]
	v_mfma_f32_16x16x32_bf16 v[32:35], v[236:239], v[168:171], v[32:35]
	v_mfma_f32_16x16x32_bf16 v[20:23], v[214:217], v[198:201], v[20:23]
	v_mfma_f32_16x16x32_bf16 v[16:19], v[236:239], v[198:201], v[16:19]
	v_mfma_f32_16x16x32_bf16 v[4:7], v[214:217], v[206:209], v[4:7]
	v_mfma_f32_16x16x32_bf16 v[0:3], v[236:239], v[206:209], v[0:3]
	s_add_i32 s88, 0, 0x18000
	v_add_u32_e32 v152, s88, v191
	s_barrier
	ds_read_b128 v[128:131], v152
	ds_read_b128 v[132:135], v152 offset:1024
	ds_read_b128 v[148:151], v152 offset:2048
	ds_read_b128 v[152:155], v152 offset:3072
	s_add_u32 s28, s70, 0x40000
	s_addc_u32 s29, s71, 0
	s_mov_b32 m0, s75
	ds_read_b128 v[156:159], v192 offset:32768
	ds_read_b128 v[164:167], v192 offset:34816
	ds_read_b128 v[194:197], v192 offset:36864
	ds_read_b128 v[202:205], v192 offset:38912
	ds_read_b128 v[160:163], v192 offset:33792
	ds_read_b128 v[168:171], v192 offset:35840
	ds_read_b128 v[198:201], v192 offset:37888
	ds_read_b128 v[206:209], v192 offset:39936
	global_load_lds_dwordx4 v136, s[28:29]
	s_mov_b32 m0, s76
	s_nop 0
	global_load_lds_dwordx4 v140, s[28:29]
	s_waitcnt lgkmcnt(8)
	s_barrier
	s_waitcnt lgkmcnt(7)
	v_mfma_f32_16x16x32_bf16 v[124:127], v[128:131], v[156:159], v[124:127]
	v_mfma_f32_16x16x32_bf16 v[120:123], v[148:151], v[156:159], v[120:123]
	s_waitcnt lgkmcnt(6)
	v_mfma_f32_16x16x32_bf16 v[108:111], v[128:131], v[164:167], v[108:111]
	v_mfma_f32_16x16x32_bf16 v[104:107], v[148:151], v[164:167], v[104:107]
	s_waitcnt lgkmcnt(5)
	v_mfma_f32_16x16x32_bf16 v[92:95], v[128:131], v[194:197], v[92:95]
	v_mfma_f32_16x16x32_bf16 v[88:91], v[148:151], v[194:197], v[88:91]
	s_waitcnt lgkmcnt(4)
	v_mfma_f32_16x16x32_bf16 v[76:79], v[128:131], v[202:205], v[76:79]
	v_mfma_f32_16x16x32_bf16 v[72:75], v[148:151], v[202:205], v[72:75]
	s_waitcnt lgkmcnt(3)
	v_mfma_f32_16x16x32_bf16 v[124:127], v[132:135], v[160:163], v[124:127]
	v_mfma_f32_16x16x32_bf16 v[120:123], v[152:155], v[160:163], v[120:123]
	s_waitcnt lgkmcnt(2)
	v_mfma_f32_16x16x32_bf16 v[108:111], v[132:135], v[168:171], v[108:111]
	v_mfma_f32_16x16x32_bf16 v[104:107], v[152:155], v[168:171], v[104:107]
	s_waitcnt lgkmcnt(1)
	v_mfma_f32_16x16x32_bf16 v[92:95], v[132:135], v[198:201], v[92:95]
	v_mfma_f32_16x16x32_bf16 v[88:91], v[152:155], v[198:201], v[88:91]
	s_waitcnt lgkmcnt(0)
	v_mfma_f32_16x16x32_bf16 v[76:79], v[132:135], v[206:209], v[76:79]
	v_mfma_f32_16x16x32_bf16 v[72:75], v[152:155], v[206:209], v[72:75]
	s_barrier
	s_add_i32 s98, 0, 0x1c000
	s_add_i32 s28, s88, s72
	v_add_u32_e32 v174, s98, v191
	s_add_i32 m0, s28, 0xffffff80
	ds_read_b128 v[210:213], v174
	ds_read_b128 v[214:217], v174 offset:1024
	ds_read_b128 v[232:235], v174 offset:2048
	ds_read_b128 v[236:239], v174 offset:3072
	global_load_lds_dwordx4 v138, s[68:69] offset:128
	s_add_i32 m0, s28, 0x1f80
	s_nop 0
	global_load_lds_dwordx4 v142, s[68:69] offset:128
	s_barrier
	s_waitcnt lgkmcnt(3)
	v_mfma_f32_16x16x32_bf16 v[116:119], v[210:213], v[156:159], v[116:119]
	s_waitcnt lgkmcnt(1)
	v_mfma_f32_16x16x32_bf16 v[112:115], v[232:235], v[156:159], v[112:115]
	v_mfma_f32_16x16x32_bf16 v[100:103], v[210:213], v[164:167], v[100:103]
	v_mfma_f32_16x16x32_bf16 v[96:99], v[232:235], v[164:167], v[96:99]
	v_mfma_f32_16x16x32_bf16 v[84:87], v[210:213], v[194:197], v[84:87]
	v_mfma_f32_16x16x32_bf16 v[80:83], v[232:235], v[194:197], v[80:83]
	v_mfma_f32_16x16x32_bf16 v[68:71], v[210:213], v[202:205], v[68:71]
	v_mfma_f32_16x16x32_bf16 v[64:67], v[232:235], v[202:205], v[64:67]
	v_mfma_f32_16x16x32_bf16 v[116:119], v[214:217], v[160:163], v[116:119]
	s_waitcnt lgkmcnt(0)
	v_mfma_f32_16x16x32_bf16 v[112:115], v[236:239], v[160:163], v[112:115]
	v_mfma_f32_16x16x32_bf16 v[100:103], v[214:217], v[168:171], v[100:103]
	v_mfma_f32_16x16x32_bf16 v[96:99], v[236:239], v[168:171], v[96:99]
	v_mfma_f32_16x16x32_bf16 v[84:87], v[214:217], v[198:201], v[84:87]
	v_mfma_f32_16x16x32_bf16 v[80:83], v[236:239], v[198:201], v[80:83]
	v_mfma_f32_16x16x32_bf16 v[68:71], v[214:217], v[206:209], v[68:71]
	v_mfma_f32_16x16x32_bf16 v[64:67], v[236:239], v[206:209], v[64:67]
	s_add_i32 m0, s79, 0xffffff80
	s_barrier
	ds_read_b128 v[156:159], v192 offset:49152
	ds_read_b128 v[164:167], v192 offset:51200
	ds_read_b128 v[194:197], v192 offset:53248
	ds_read_b128 v[202:205], v192 offset:55296
	ds_read_b128 v[160:163], v192 offset:50176
	ds_read_b128 v[168:171], v192 offset:52224
	ds_read_b128 v[198:201], v192 offset:54272
	ds_read_b128 v[206:209], v192 offset:56320
	global_load_lds_dwordx4 v136, s[70:71] offset:128
	s_add_i32 m0, s80, 0xffffff80
	s_nop 0
	global_load_lds_dwordx4 v140, s[70:71] offset:128
	s_barrier
	s_waitcnt lgkmcnt(7)
	v_mfma_f32_16x16x32_bf16 v[60:63], v[128:131], v[156:159], v[60:63]
	v_mfma_f32_16x16x32_bf16 v[56:59], v[148:151], v[156:159], v[56:59]
	s_waitcnt lgkmcnt(6)
	v_mfma_f32_16x16x32_bf16 v[44:47], v[128:131], v[164:167], v[44:47]
	v_mfma_f32_16x16x32_bf16 v[40:43], v[148:151], v[164:167], v[40:43]
	s_waitcnt lgkmcnt(5)
	v_mfma_f32_16x16x32_bf16 v[28:31], v[128:131], v[194:197], v[28:31]
	v_mfma_f32_16x16x32_bf16 v[24:27], v[148:151], v[194:197], v[24:27]
	s_waitcnt lgkmcnt(4)
	v_mfma_f32_16x16x32_bf16 v[12:15], v[128:131], v[202:205], v[12:15]
	v_mfma_f32_16x16x32_bf16 v[8:11], v[148:151], v[202:205], v[8:11]
	s_waitcnt lgkmcnt(3)
	v_mfma_f32_16x16x32_bf16 v[60:63], v[132:135], v[160:163], v[60:63]
	v_mfma_f32_16x16x32_bf16 v[56:59], v[152:155], v[160:163], v[56:59]
	s_waitcnt lgkmcnt(2)
	v_mfma_f32_16x16x32_bf16 v[44:47], v[132:135], v[168:171], v[44:47]
	v_mfma_f32_16x16x32_bf16 v[40:43], v[152:155], v[168:171], v[40:43]
	s_waitcnt lgkmcnt(1)
	v_mfma_f32_16x16x32_bf16 v[28:31], v[132:135], v[198:201], v[28:31]
	v_mfma_f32_16x16x32_bf16 v[24:27], v[152:155], v[198:201], v[24:27]
	s_waitcnt lgkmcnt(0)
	v_mfma_f32_16x16x32_bf16 v[12:15], v[132:135], v[206:209], v[12:15]
	v_mfma_f32_16x16x32_bf16 v[8:11], v[152:155], v[206:209], v[8:11]
	s_barrier
	s_add_u32 s28, s68, 0x40080
	s_addc_u32 s29, s69, 0
	s_add_i32 s68, s98, s72
	s_mov_b32 m0, s68
	s_nop 0
	global_load_lds_dwordx4 v138, s[28:29]
	s_add_i32 m0, s68, 0x2000
	s_nop 0
	global_load_lds_dwordx4 v142, s[28:29]
	s_waitcnt vmcnt(6)
	s_barrier
	v_mfma_f32_16x16x32_bf16 v[52:55], v[210:213], v[156:159], v[52:55]
	v_mfma_f32_16x16x32_bf16 v[48:51], v[232:235], v[156:159], v[48:51]
	v_mfma_f32_16x16x32_bf16 v[36:39], v[210:213], v[164:167], v[36:39]
	v_mfma_f32_16x16x32_bf16 v[32:35], v[232:235], v[164:167], v[32:35]
	v_mfma_f32_16x16x32_bf16 v[20:23], v[210:213], v[194:197], v[20:23]
	v_mfma_f32_16x16x32_bf16 v[16:19], v[232:235], v[194:197], v[16:19]
	v_mfma_f32_16x16x32_bf16 v[4:7], v[210:213], v[202:205], v[4:7]
	v_mfma_f32_16x16x32_bf16 v[0:3], v[232:235], v[202:205], v[0:3]
	v_mfma_f32_16x16x32_bf16 v[52:55], v[214:217], v[160:163], v[52:55]
	v_mfma_f32_16x16x32_bf16 v[48:51], v[236:239], v[160:163], v[48:51]
	v_mfma_f32_16x16x32_bf16 v[36:39], v[214:217], v[168:171], v[36:39]
	v_mfma_f32_16x16x32_bf16 v[32:35], v[236:239], v[168:171], v[32:35]
	v_mfma_f32_16x16x32_bf16 v[20:23], v[214:217], v[198:201], v[20:23]
	v_mfma_f32_16x16x32_bf16 v[16:19], v[236:239], v[198:201], v[16:19]
	v_mfma_f32_16x16x32_bf16 v[4:7], v[214:217], v[206:209], v[4:7]
	v_mfma_f32_16x16x32_bf16 v[0:3], v[236:239], v[206:209], v[0:3]
	s_add_i32 vcc_lo, vcc_lo, 2
	s_add_u32 s66, s66, 0x100
	s_addc_u32 s67, s67, 0
	s_add_u32 s85, s85, 0x100
	s_addc_u32 s91, s91, 0
	s_cmp_lt_u32 vcc_lo, 14
	s_barrier
	s_cbranch_scc1 .LBB0_134
	s_lshl_b32 s4, s4, 8
	v_mov_b32_e32 v176, v175
	v_mov_b32_e32 v188, v190
	s_add_i32 s4, s4, s77
	s_cmp_gt_i32 s6, 7
	v_add_u32_e32 v148, s4, v176
	v_lshlrev_b32_e32 v128, 2, v188
	v_ashrrev_i32_e32 v129, 31, v128
	v_ashrrev_i32_e32 v149, 31, v148
	v_lshl_add_u64 v[128:129], v[128:129], 2, s[8:9]
	v_lshlrev_b64 v[130:131], 6, v[148:149]
	v_add_u32_e32 v166, 16, v148
	v_lshl_add_u64 v[130:131], v[128:129], 0, v[130:131]
	v_ashrrev_i32_e32 v167, 31, v166
	global_load_dwordx4 v[160:163], v[130:131], off
	v_lshlrev_b64 v[130:131], 6, v[166:167]
	v_lshl_add_u64 v[130:131], v[128:129], 0, v[130:131]
	global_load_dwordx4 v[168:171], v[130:131], off
	v_add_u32_e32 v164, 32, v148
	v_ashrrev_i32_e32 v165, 31, v164
	v_lshlrev_b64 v[130:131], 6, v[164:165]
	v_add_u32_e32 v158, 48, v148
	v_lshl_add_u64 v[130:131], v[128:129], 0, v[130:131]
	v_ashrrev_i32_e32 v159, 31, v158
	global_load_dwordx4 v[194:197], v[130:131], off
	v_lshlrev_b64 v[130:131], 6, v[158:159]
	v_lshl_add_u64 v[130:131], v[128:129], 0, v[130:131]
	global_load_dwordx4 v[198:201], v[130:131], off
	v_add_u32_e32 v156, 0x80, v148
	v_ashrrev_i32_e32 v157, 31, v156
	v_lshlrev_b64 v[130:131], 6, v[156:157]
	v_add_u32_e32 v154, 0x90, v148
	v_lshl_add_u64 v[130:131], v[128:129], 0, v[130:131]
	v_ashrrev_i32_e32 v155, 31, v154
	global_load_dwordx4 v[202:205], v[130:131], off
	v_lshlrev_b64 v[130:131], 6, v[154:155]
	v_add_u32_e32 v152, 0xa0, v148
	v_lshl_add_u64 v[130:131], v[128:129], 0, v[130:131]
	v_ashrrev_i32_e32 v153, 31, v152
	global_load_dwordx4 v[206:209], v[130:131], off
	v_lshlrev_b64 v[130:131], 6, v[152:153]
	v_add_u32_e32 v150, 0xb0, v148
	v_lshl_add_u64 v[130:131], v[128:129], 0, v[130:131]
	v_ashrrev_i32_e32 v151, 31, v150
	global_load_dwordx4 v[132:135], v[130:131], off
	v_lshlrev_b64 v[130:131], 6, v[150:151]
	v_lshl_add_u64 v[128:129], v[128:129], 0, v[130:131]
	global_load_dwordx4 v[128:131], v[128:129], off
	s_cselect_b64 s[66:67], -1, 0
	s_lshl_b32 s7, s6, 8
	s_add_i32 s7, s81, s7
	s_cmp_lt_i32 s6, 8
	s_mov_b64 s[68:69], -1
	s_waitcnt vmcnt(0)
	v_mov_b32_e32 v172, v161
	v_mov_b32_e32 v173, v162
	v_mov_b32_e32 v161, v163
	v_mov_b32_e32 v162, v169
	v_mov_b32_e32 v163, v170
	v_mov_b32_e32 v169, v171
	v_pk_add_f32 v[160:161], v[172:173], v[160:161]
	v_pk_add_f32 v[162:163], v[162:163], v[168:169]
	v_mov_b32_e32 v169, v160
	v_mov_b32_e32 v168, v162
	v_mov_b32_e32 v160, v163
	v_pk_add_f32 v[160:161], v[168:169], v[160:161]
	ds_bpermute_b32 v163, v219, v161
	ds_bpermute_b32 v162, v219, v160
	s_waitcnt lgkmcnt(0)
	v_pk_add_f32 v[160:161], v[160:161], v[162:163]
	ds_bpermute_b32 v163, v218, v161
	ds_bpermute_b32 v162, v218, v160
	s_waitcnt lgkmcnt(0)
	v_pk_add_f32 v[160:161], v[160:161], v[162:163]
	s_nop 0
	v_pk_fma_f32 v[172:173], v[160:161], s[30:31], v[178:179] op_sel_hi:[1,0,0]
	v_mov_b32_e32 v162, v199
	v_mul_f32_e32 v160, 0x4b800000, v173
	v_cmp_gt_f32_e32 vcc, s86, v173
	v_mov_b32_e32 v163, v200
	v_mov_b32_e32 v199, v201
	v_cndmask_b32_e32 v160, v173, v160, vcc
	v_rsq_f32_e32 v160, v160
	v_pk_add_f32 v[162:163], v[162:163], v[198:199]
	v_cmp_gt_f32_e64 s[4:5], s86, v172
	v_mov_b32_e32 v168, v162
	v_mul_f32_e32 v161, 0x45800000, v160
	v_cndmask_b32_e32 v174, v160, v161, vcc
	v_mov_b32_e32 v160, v195
	v_mov_b32_e32 v161, v196
	v_mov_b32_e32 v195, v197
	v_pk_add_f32 v[160:161], v[160:161], v[194:195]
	s_nop 0
	v_mov_b32_e32 v169, v160
	v_mov_b32_e32 v160, v163
	v_pk_add_f32 v[160:161], v[168:169], v[160:161]
	ds_bpermute_b32 v163, v219, v161
	ds_bpermute_b32 v162, v219, v160
	s_waitcnt lgkmcnt(0)
	v_pk_add_f32 v[168:169], v[160:161], v[162:163]
	v_mov_b32_e32 v160, v203
	v_mov_b32_e32 v161, v204
	v_mov_b32_e32 v203, v205
	v_mov_b32_e32 v162, v207
	v_mov_b32_e32 v163, v208
	v_mov_b32_e32 v207, v209
	v_pk_add_f32 v[160:161], v[160:161], v[202:203]
	v_pk_add_f32 v[162:163], v[162:163], v[206:207]
	v_mov_b32_e32 v195, v160
	v_mov_b32_e32 v194, v162
	v_mov_b32_e32 v160, v163
	v_pk_add_f32 v[160:161], v[194:195], v[160:161]
	v_mov_b32_e32 v194, v133
	v_mov_b32_e32 v195, v134
	v_mov_b32_e32 v133, v135
	v_mov_b32_e32 v134, v129
	v_mov_b32_e32 v135, v130
	v_mov_b32_e32 v129, v131
	v_pk_add_f32 v[132:133], v[194:195], v[132:133]
	v_pk_add_f32 v[128:129], v[134:135], v[128:129]
	v_mov_b32_e32 v131, v132
	v_mov_b32_e32 v130, v128
	v_mov_b32_e32 v132, v129
	v_pk_add_f32 v[128:129], v[130:131], v[132:133]
	ds_bpermute_b32 v163, v219, v161
	ds_bpermute_b32 v162, v219, v160
	ds_bpermute_b32 v131, v219, v129
	ds_bpermute_b32 v130, v219, v128
	ds_bpermute_b32 v171, v218, v169
	ds_bpermute_b32 v170, v218, v168
	s_waitcnt lgkmcnt(4)
	v_pk_add_f32 v[160:161], v[160:161], v[162:163]
	ds_bpermute_b32 v163, v218, v161
	s_waitcnt lgkmcnt(3)
	v_pk_add_f32 v[132:133], v[128:129], v[130:131]
	ds_bpermute_b32 v162, v218, v160
	ds_bpermute_b32 v135, v218, v133
	ds_bpermute_b32 v134, v218, v132
	v_lshlrev_b32_e32 v128, 3, v188
	v_add_u32_e32 v130, s7, v128
	v_lshlrev_b64 v[188:189], 11, v[148:149]
	v_ashrrev_i32_e32 v131, 31, v130
	s_cbranch_scc1 .LBB0_137
	v_mul_f32_e32 v196, v120, v174
	v_mul_f32_e32 v197, v121, v174
	v_mul_f32_e32 v198, v122, v174
	v_mul_f32_e32 v199, v123, v174
	v_mul_f32_e32 v129, v124, v174
	v_mul_f32_e32 v149, v125, v174
	v_mul_f32_e32 v173, v126, v174
	v_mul_f32_e32 v193, v127, v174
	v_cvt_pk_bf16_f32 v194, v129, v149
	v_cvt_pk_bf16_f32 v195, v173, v193
	v_cvt_pk_bf16_f32 v196, v196, v197
	v_cvt_pk_bf16_f32 v197, v198, v199
	v_lshl_add_u64 v[198:199], s[12:13], 0, v[188:189]
	v_lshl_add_u64 v[198:199], v[130:131], 1, v[198:199]
	global_store_dwordx4 v[198:199], v[194:197], off
	s_mov_b64 s[68:69], 0
	v_mul_f32_e32 v129, v116, v174
	v_mul_f32_e32 v196, v112, v174
	v_mul_f32_e32 v197, v113, v174
	v_mul_f32_e32 v149, v117, v174
	v_mul_f32_e32 v173, v118, v174
	v_mul_f32_e32 v193, v119, v174
	v_mul_f32_e32 v200, v114, v174
	v_mul_f32_e32 v201, v115, v174
	v_cvt_pk_bf16_f32 v194, v129, v149
	v_cvt_pk_bf16_f32 v195, v173, v193
	v_cvt_pk_bf16_f32 v196, v196, v197
	v_cvt_pk_bf16_f32 v197, v200, v201
	global_store_dwordx4 v[198:199], v[194:197], off offset:256

.LBB0_413:
	s_add_i32 vcc_lo, s62, 2
	s_add_u32 s4, s18, 0x100
	s_addc_u32 s5, s19, 0
	s_add_i32 s28, 0, 0x10000
	v_add_u32_e32 v140, s28, v164
	ds_read_b128 v[128:131], v140
	ds_read_b128 v[132:135], v140 offset:1024
	ds_read_b128 v[136:139], v140 offset:2048
	ds_read_b128 v[140:143], v140 offset:3072
	s_cmp_eq_u32 s13, s62
	s_cselect_b32 s62, s6, s85
	s_cselect_b32 s65, s17, s5
	s_cselect_b32 s64, s16, s4
	s_cselect_b32 s63, s7, s91
	s_add_i32 m0, s69, 0xc000
	ds_read_b128 v[154:157], v165
	ds_read_b128 v[166:169], v165 offset:2048
	ds_read_b128 v[188:191], v165 offset:4096
	ds_read_b128 v[196:199], v165 offset:6144
	ds_read_b128 v[158:161], v165 offset:1024
	ds_read_b128 v[170:173], v165 offset:3072
	ds_read_b128 v[192:195], v165 offset:5120
	ds_read_b128 v[200:203], v165 offset:7168
	global_load_lds_dwordx4 v150, s[18:19]
	s_add_i32 m0, s69, 0xe000
	s_nop 0
	global_load_lds_dwordx4 v152, s[18:19]
	s_waitcnt lgkmcnt(8)
	s_barrier
	s_waitcnt lgkmcnt(7)
	v_mfma_f32_16x16x32_bf16 v[124:127], v[128:131], v[154:157], v[124:127]
	v_mfma_f32_16x16x32_bf16 v[120:123], v[136:139], v[154:157], v[120:123]
	s_waitcnt lgkmcnt(6)
	v_mfma_f32_16x16x32_bf16 v[108:111], v[128:131], v[166:169], v[108:111]
	v_mfma_f32_16x16x32_bf16 v[104:107], v[136:139], v[166:169], v[104:107]
	s_waitcnt lgkmcnt(5)
	v_mfma_f32_16x16x32_bf16 v[92:95], v[128:131], v[188:191], v[92:95]
	v_mfma_f32_16x16x32_bf16 v[88:91], v[136:139], v[188:191], v[88:91]
	s_waitcnt lgkmcnt(4)
	v_mfma_f32_16x16x32_bf16 v[76:79], v[128:131], v[196:199], v[76:79]
	v_mfma_f32_16x16x32_bf16 v[72:75], v[136:139], v[196:199], v[72:75]
	s_waitcnt lgkmcnt(3)
	v_mfma_f32_16x16x32_bf16 v[124:127], v[132:135], v[158:161], v[124:127]
	v_mfma_f32_16x16x32_bf16 v[120:123], v[140:143], v[158:161], v[120:123]
	s_waitcnt lgkmcnt(2)
	v_mfma_f32_16x16x32_bf16 v[108:111], v[132:135], v[170:173], v[108:111]
	v_mfma_f32_16x16x32_bf16 v[104:107], v[140:143], v[170:173], v[104:107]
	s_waitcnt lgkmcnt(1)
	v_mfma_f32_16x16x32_bf16 v[92:95], v[132:135], v[192:195], v[92:95]
	v_mfma_f32_16x16x32_bf16 v[88:91], v[140:143], v[192:195], v[88:91]
	s_waitcnt lgkmcnt(0)
	v_mfma_f32_16x16x32_bf16 v[76:79], v[132:135], v[200:203], v[76:79]
	v_mfma_f32_16x16x32_bf16 v[72:75], v[140:143], v[200:203], v[72:75]
	s_barrier
	s_add_i32 s29, 0, 0x14000
	v_add_u32_e32 v174, s29, v164
	s_add_i32 s18, s28, s68
	ds_read_b128 v[204:207], v174
	ds_read_b128 v[208:211], v174 offset:1024
	ds_read_b128 v[212:215], v174 offset:2048
	ds_read_b128 v[232:235], v174 offset:3072
	s_mov_b32 m0, s18
	s_nop 0
	global_load_lds_dwordx4 v176, s[62:63]
	s_add_i32 m0, s18, 0x2000
	s_nop 0
	global_load_lds_dwordx4 v148, s[62:63]
	s_barrier
	s_waitcnt lgkmcnt(3)
	v_mfma_f32_16x16x32_bf16 v[116:119], v[204:207], v[154:157], v[116:119]
	s_waitcnt lgkmcnt(1)
	v_mfma_f32_16x16x32_bf16 v[112:115], v[212:215], v[154:157], v[112:115]
	v_mfma_f32_16x16x32_bf16 v[100:103], v[204:207], v[166:169], v[100:103]
	v_mfma_f32_16x16x32_bf16 v[96:99], v[212:215], v[166:169], v[96:99]
	v_mfma_f32_16x16x32_bf16 v[84:87], v[204:207], v[188:191], v[84:87]
	v_mfma_f32_16x16x32_bf16 v[80:83], v[212:215], v[188:191], v[80:83]
	v_mfma_f32_16x16x32_bf16 v[68:71], v[204:207], v[196:199], v[68:71]
	v_mfma_f32_16x16x32_bf16 v[64:67], v[212:215], v[196:199], v[64:67]
	v_mfma_f32_16x16x32_bf16 v[116:119], v[208:211], v[158:161], v[116:119]
	s_waitcnt lgkmcnt(0)
	v_mfma_f32_16x16x32_bf16 v[112:115], v[232:235], v[158:161], v[112:115]
	v_mfma_f32_16x16x32_bf16 v[100:103], v[208:211], v[170:173], v[100:103]
	v_mfma_f32_16x16x32_bf16 v[96:99], v[232:235], v[170:173], v[96:99]
	v_mfma_f32_16x16x32_bf16 v[84:87], v[208:211], v[192:195], v[84:87]
	v_mfma_f32_16x16x32_bf16 v[80:83], v[232:235], v[192:195], v[80:83]
	v_mfma_f32_16x16x32_bf16 v[68:71], v[208:211], v[200:203], v[68:71]
	v_mfma_f32_16x16x32_bf16 v[64:67], v[232:235], v[200:203], v[64:67]
	s_mov_b32 m0, s69
	s_barrier
	ds_read_b128 v[154:157], v165 offset:16384
	ds_read_b128 v[166:169], v165 offset:18432
	ds_read_b128 v[188:191], v165 offset:20480
	ds_read_b128 v[196:199], v165 offset:22528
	ds_read_b128 v[158:161], v165 offset:17408
	ds_read_b128 v[170:173], v165 offset:19456
	ds_read_b128 v[192:195], v165 offset:21504
	ds_read_b128 v[200:203], v165 offset:23552
	global_load_lds_dwordx4 v144, s[64:65]
	s_mov_b32 m0, s70
	s_nop 0
	global_load_lds_dwordx4 v146, s[64:65]
	s_barrier
	s_waitcnt lgkmcnt(7)
	v_mfma_f32_16x16x32_bf16 v[60:63], v[128:131], v[154:157], v[60:63]
	v_mfma_f32_16x16x32_bf16 v[56:59], v[136:139], v[154:157], v[56:59]
	s_waitcnt lgkmcnt(6)
	v_mfma_f32_16x16x32_bf16 v[44:47], v[128:131], v[166:169], v[44:47]
	v_mfma_f32_16x16x32_bf16 v[40:43], v[136:139], v[166:169], v[40:43]
	s_waitcnt lgkmcnt(5)
	v_mfma_f32_16x16x32_bf16 v[28:31], v[128:131], v[188:191], v[28:31]
	v_mfma_f32_16x16x32_bf16 v[24:27], v[136:139], v[188:191], v[24:27]
	s_waitcnt lgkmcnt(4)
	v_mfma_f32_16x16x32_bf16 v[12:15], v[128:131], v[196:199], v[12:15]
	v_mfma_f32_16x16x32_bf16 v[8:11], v[136:139], v[196:199], v[8:11]
	s_waitcnt lgkmcnt(3)
	v_mfma_f32_16x16x32_bf16 v[60:63], v[132:135], v[158:161], v[60:63]
	v_mfma_f32_16x16x32_bf16 v[56:59], v[140:143], v[158:161], v[56:59]
	s_waitcnt lgkmcnt(2)
	v_mfma_f32_16x16x32_bf16 v[44:47], v[132:135], v[170:173], v[44:47]
	v_mfma_f32_16x16x32_bf16 v[40:43], v[140:143], v[170:173], v[40:43]
	s_waitcnt lgkmcnt(1)
	v_mfma_f32_16x16x32_bf16 v[28:31], v[132:135], v[192:195], v[28:31]
	v_mfma_f32_16x16x32_bf16 v[24:27], v[140:143], v[192:195], v[24:27]
	s_waitcnt lgkmcnt(0)
	v_mfma_f32_16x16x32_bf16 v[12:15], v[132:135], v[200:203], v[12:15]
	v_mfma_f32_16x16x32_bf16 v[8:11], v[140:143], v[200:203], v[8:11]
	s_barrier
	s_add_u32 s18, s62, 0x18000
	s_addc_u32 s19, s63, 0
	s_add_i32 s28, s29, s68
	s_mov_b32 m0, s28
	s_nop 0
	global_load_lds_dwordx4 v176, s[18:19]
	s_add_i32 m0, s28, 0x2000
	s_nop 0
	global_load_lds_dwordx4 v148, s[18:19]
	s_waitcnt vmcnt(6)
	s_barrier
	v_mfma_f32_16x16x32_bf16 v[52:55], v[204:207], v[154:157], v[52:55]
	v_mfma_f32_16x16x32_bf16 v[48:51], v[212:215], v[154:157], v[48:51]
	v_mfma_f32_16x16x32_bf16 v[36:39], v[204:207], v[166:169], v[36:39]
	v_mfma_f32_16x16x32_bf16 v[32:35], v[212:215], v[166:169], v[32:35]
	v_mfma_f32_16x16x32_bf16 v[20:23], v[204:207], v[188:191], v[20:23]
	v_mfma_f32_16x16x32_bf16 v[16:19], v[212:215], v[188:191], v[16:19]
	v_mfma_f32_16x16x32_bf16 v[4:7], v[204:207], v[196:199], v[4:7]
	v_mfma_f32_16x16x32_bf16 v[0:3], v[212:215], v[196:199], v[0:3]
	v_mfma_f32_16x16x32_bf16 v[52:55], v[208:211], v[158:161], v[52:55]
	v_mfma_f32_16x16x32_bf16 v[48:51], v[232:235], v[158:161], v[48:51]
	v_mfma_f32_16x16x32_bf16 v[36:39], v[208:211], v[170:173], v[36:39]
	v_mfma_f32_16x16x32_bf16 v[32:35], v[232:235], v[170:173], v[32:35]
	v_mfma_f32_16x16x32_bf16 v[20:23], v[208:211], v[192:195], v[20:23]
	v_mfma_f32_16x16x32_bf16 v[16:19], v[232:235], v[192:195], v[16:19]
	v_mfma_f32_16x16x32_bf16 v[4:7], v[208:211], v[200:203], v[4:7]
	v_mfma_f32_16x16x32_bf16 v[0:3], v[232:235], v[200:203], v[0:3]
	s_add_i32 s28, 0, 0x18000
	v_add_u32_e32 v140, s28, v164
	s_barrier
	ds_read_b128 v[128:131], v140
	ds_read_b128 v[132:135], v140 offset:1024
	ds_read_b128 v[136:139], v140 offset:2048
	ds_read_b128 v[140:143], v140 offset:3072
	s_add_u32 s18, s64, 0x18000
	s_addc_u32 s19, s65, 0
	s_mov_b32 m0, s71
	ds_read_b128 v[154:157], v165 offset:32768
	ds_read_b128 v[166:169], v165 offset:34816
	ds_read_b128 v[188:191], v165 offset:36864
	ds_read_b128 v[196:199], v165 offset:38912
	ds_read_b128 v[158:161], v165 offset:33792
	ds_read_b128 v[170:173], v165 offset:35840
	ds_read_b128 v[192:195], v165 offset:37888
	ds_read_b128 v[200:203], v165 offset:39936
	global_load_lds_dwordx4 v144, s[18:19]
	s_mov_b32 m0, s72
	s_nop 0
	global_load_lds_dwordx4 v146, s[18:19]
	s_waitcnt lgkmcnt(8)
	s_barrier
	s_waitcnt lgkmcnt(7)
	v_mfma_f32_16x16x32_bf16 v[124:127], v[128:131], v[154:157], v[124:127]
	v_mfma_f32_16x16x32_bf16 v[120:123], v[136:139], v[154:157], v[120:123]
	s_waitcnt lgkmcnt(6)
	v_mfma_f32_16x16x32_bf16 v[108:111], v[128:131], v[166:169], v[108:111]
	v_mfma_f32_16x16x32_bf16 v[104:107], v[136:139], v[166:169], v[104:107]
	s_waitcnt lgkmcnt(5)
	v_mfma_f32_16x16x32_bf16 v[92:95], v[128:131], v[188:191], v[92:95]
	v_mfma_f32_16x16x32_bf16 v[88:91], v[136:139], v[188:191], v[88:91]
	s_waitcnt lgkmcnt(4)
	v_mfma_f32_16x16x32_bf16 v[76:79], v[128:131], v[196:199], v[76:79]
	v_mfma_f32_16x16x32_bf16 v[72:75], v[136:139], v[196:199], v[72:75]
	s_waitcnt lgkmcnt(3)
	v_mfma_f32_16x16x32_bf16 v[124:127], v[132:135], v[158:161], v[124:127]
	v_mfma_f32_16x16x32_bf16 v[120:123], v[140:143], v[158:161], v[120:123]
	s_waitcnt lgkmcnt(2)
	v_mfma_f32_16x16x32_bf16 v[108:111], v[132:135], v[170:173], v[108:111]
	v_mfma_f32_16x16x32_bf16 v[104:107], v[140:143], v[170:173], v[104:107]
	s_waitcnt lgkmcnt(1)
	v_mfma_f32_16x16x32_bf16 v[92:95], v[132:135], v[192:195], v[92:95]
	v_mfma_f32_16x16x32_bf16 v[88:91], v[140:143], v[192:195], v[88:91]
	s_waitcnt lgkmcnt(0)
	v_mfma_f32_16x16x32_bf16 v[76:79], v[132:135], v[200:203], v[76:79]
	v_mfma_f32_16x16x32_bf16 v[72:75], v[140:143], v[200:203], v[72:75]
	s_barrier
	s_add_i32 s29, 0, 0x1c000
	s_add_i32 s18, s28, s68
	v_add_u32_e32 v232, s29, v164
	s_add_i32 m0, s18, 0xffffff80
	ds_read_b128 v[204:207], v232
	ds_read_b128 v[208:211], v232 offset:1024
	ds_read_b128 v[212:215], v232 offset:2048
	ds_read_b128 v[232:235], v232 offset:3072
	global_load_lds_dwordx4 v176, s[62:63] offset:128
	s_add_i32 m0, s18, 0x1f80
	s_nop 0
	global_load_lds_dwordx4 v148, s[62:63] offset:128
	s_barrier
	s_waitcnt lgkmcnt(3)
	v_mfma_f32_16x16x32_bf16 v[116:119], v[204:207], v[154:157], v[116:119]
	s_waitcnt lgkmcnt(1)
	v_mfma_f32_16x16x32_bf16 v[112:115], v[212:215], v[154:157], v[112:115]
	v_mfma_f32_16x16x32_bf16 v[100:103], v[204:207], v[166:169], v[100:103]
	v_mfma_f32_16x16x32_bf16 v[96:99], v[212:215], v[166:169], v[96:99]
	v_mfma_f32_16x16x32_bf16 v[84:87], v[204:207], v[188:191], v[84:87]
	v_mfma_f32_16x16x32_bf16 v[80:83], v[212:215], v[188:191], v[80:83]
	v_mfma_f32_16x16x32_bf16 v[68:71], v[204:207], v[196:199], v[68:71]
	v_mfma_f32_16x16x32_bf16 v[64:67], v[212:215], v[196:199], v[64:67]
	v_mfma_f32_16x16x32_bf16 v[116:119], v[208:211], v[158:161], v[116:119]
	s_waitcnt lgkmcnt(0)
	v_mfma_f32_16x16x32_bf16 v[112:115], v[232:235], v[158:161], v[112:115]
	v_mfma_f32_16x16x32_bf16 v[100:103], v[208:211], v[170:173], v[100:103]
	v_mfma_f32_16x16x32_bf16 v[96:99], v[232:235], v[170:173], v[96:99]
	v_mfma_f32_16x16x32_bf16 v[84:87], v[208:211], v[192:195], v[84:87]
	v_mfma_f32_16x16x32_bf16 v[80:83], v[232:235], v[192:195], v[80:83]
	v_mfma_f32_16x16x32_bf16 v[68:71], v[208:211], v[200:203], v[68:71]
	v_mfma_f32_16x16x32_bf16 v[64:67], v[232:235], v[200:203], v[64:67]
	s_add_i32 m0, s75, 0xffffff80
	s_barrier
	ds_read_b128 v[154:157], v165 offset:49152
	ds_read_b128 v[166:169], v165 offset:51200
	ds_read_b128 v[188:191], v165 offset:53248
	ds_read_b128 v[196:199], v165 offset:55296
	ds_read_b128 v[158:161], v165 offset:50176
	ds_read_b128 v[170:173], v165 offset:52224
	ds_read_b128 v[192:195], v165 offset:54272
	ds_read_b128 v[200:203], v165 offset:56320
	global_load_lds_dwordx4 v144, s[64:65] offset:128
	s_add_i32 m0, s76, 0xffffff80
	s_nop 0
	global_load_lds_dwordx4 v146, s[64:65] offset:128
	s_barrier
	s_waitcnt lgkmcnt(7)
	v_mfma_f32_16x16x32_bf16 v[60:63], v[128:131], v[154:157], v[60:63]
	v_mfma_f32_16x16x32_bf16 v[56:59], v[136:139], v[154:157], v[56:59]
	s_waitcnt lgkmcnt(6)
	v_mfma_f32_16x16x32_bf16 v[44:47], v[128:131], v[166:169], v[44:47]
	v_mfma_f32_16x16x32_bf16 v[40:43], v[136:139], v[166:169], v[40:43]
	s_waitcnt lgkmcnt(5)
	v_mfma_f32_16x16x32_bf16 v[28:31], v[128:131], v[188:191], v[28:31]
	v_mfma_f32_16x16x32_bf16 v[24:27], v[136:139], v[188:191], v[24:27]
	s_waitcnt lgkmcnt(4)
	v_mfma_f32_16x16x32_bf16 v[12:15], v[128:131], v[196:199], v[12:15]
	v_mfma_f32_16x16x32_bf16 v[8:11], v[136:139], v[196:199], v[8:11]
	s_waitcnt lgkmcnt(3)
	v_mfma_f32_16x16x32_bf16 v[60:63], v[132:135], v[158:161], v[60:63]
	v_mfma_f32_16x16x32_bf16 v[56:59], v[140:143], v[158:161], v[56:59]
	s_waitcnt lgkmcnt(2)
	v_mfma_f32_16x16x32_bf16 v[44:47], v[132:135], v[170:173], v[44:47]
	v_mfma_f32_16x16x32_bf16 v[40:43], v[140:143], v[170:173], v[40:43]
	s_waitcnt lgkmcnt(1)
	v_mfma_f32_16x16x32_bf16 v[28:31], v[132:135], v[192:195], v[28:31]
	v_mfma_f32_16x16x32_bf16 v[24:27], v[140:143], v[192:195], v[24:27]
	s_waitcnt lgkmcnt(0)
	v_mfma_f32_16x16x32_bf16 v[12:15], v[132:135], v[200:203], v[12:15]
	v_mfma_f32_16x16x32_bf16 v[8:11], v[140:143], v[200:203], v[8:11]
	s_barrier
	s_add_u32 s18, s62, 0x18080
	s_addc_u32 s19, s63, 0
	s_add_i32 s28, s29, s68
	s_mov_b32 m0, s28
	s_nop 0
	global_load_lds_dwordx4 v176, s[18:19]
	s_add_i32 m0, s28, 0x2000
	s_nop 0
	global_load_lds_dwordx4 v148, s[18:19]
	s_waitcnt vmcnt(6)
	s_barrier
	v_mfma_f32_16x16x32_bf16 v[52:55], v[204:207], v[154:157], v[52:55]
	v_mfma_f32_16x16x32_bf16 v[48:51], v[212:215], v[154:157], v[48:51]
	v_mfma_f32_16x16x32_bf16 v[36:39], v[204:207], v[166:169], v[36:39]
	v_mfma_f32_16x16x32_bf16 v[32:35], v[212:215], v[166:169], v[32:35]
	v_mfma_f32_16x16x32_bf16 v[20:23], v[204:207], v[188:191], v[20:23]
	v_mfma_f32_16x16x32_bf16 v[16:19], v[212:215], v[188:191], v[16:19]
	v_mfma_f32_16x16x32_bf16 v[4:7], v[204:207], v[196:199], v[4:7]
	v_mfma_f32_16x16x32_bf16 v[0:3], v[212:215], v[196:199], v[0:3]
	v_mfma_f32_16x16x32_bf16 v[52:55], v[208:211], v[158:161], v[52:55]
	v_mfma_f32_16x16x32_bf16 v[48:51], v[232:235], v[158:161], v[48:51]
	v_mfma_f32_16x16x32_bf16 v[36:39], v[208:211], v[170:173], v[36:39]
	v_mfma_f32_16x16x32_bf16 v[32:35], v[232:235], v[170:173], v[32:35]
	v_mfma_f32_16x16x32_bf16 v[20:23], v[208:211], v[192:195], v[20:23]
	v_mfma_f32_16x16x32_bf16 v[16:19], v[232:235], v[192:195], v[16:19]
	v_mfma_f32_16x16x32_bf16 v[4:7], v[208:211], v[200:203], v[4:7]
	v_mfma_f32_16x16x32_bf16 v[0:3], v[232:235], v[200:203], v[0:3]
	s_add_u32 s85, s85, 0x100
	s_addc_u32 s91, s91, 0
	s_cmp_lt_i32 vcc_lo, s67
	s_mov_b64 s[18:19], s[4:5]
	s_mov_b32 s62, vcc_lo
	s_barrier
	s_cbranch_scc1 .LBB0_413
	s_ashr_i32 s4, s66, 2
	v_mov_b32_e32 v128, v163
	v_mov_b32_e32 v166, v162
	s_cmp_eq_u32 s4, 2
	s_cbranch_scc1 .LBB0_416
	s_mul_i32 s13, s4, 0x2280000
	s_mul_hi_i32 s5, s4, 0x2280000
	s_add_u32 s18, s13, 0x5858000
	s_addc_u32 s19, s5, 0
	s_mov_b32 s62, 1.0
	s_branch .LBB0_417

.LBB0_505:
	s_add_u32 s6, s4, 0xfff80080
	s_addc_u32 s7, s5, -1
	s_add_i32 s28, 0, 0x10000
	v_add_u32_e32 v154, s28, v144
	ds_read_b128 v[138:141], v154
	ds_read_b128 v[146:149], v154 offset:1024
	ds_read_b128 v[150:153], v154 offset:2048
	ds_read_b128 v[154:157], v154 offset:3072
	s_cmp_eq_u32 s72, 28
	s_cselect_b32 s9, s10, s7
	s_cselect_b32 s8, s11, s6
	s_cselect_b32 s7, s63, s71
	s_cselect_b32 s6, s65, s70
	s_add_i32 m0, s17, 0xc000
	ds_read_b128 v[158:161], v145
	ds_read_b128 v[166:169], v145 offset:2048
	ds_read_b128 v[188:191], v145 offset:4096
	ds_read_b128 v[196:199], v145 offset:6144
	ds_read_b128 v[162:165], v145 offset:1024
	ds_read_b128 v[170:173], v145 offset:3072
	ds_read_b128 v[192:195], v145 offset:5120
	ds_read_b128 v[200:203], v145 offset:7168
	global_load_lds_dwordx4 v134, s[4:5]
	s_add_i32 m0, s17, 0xe000
	s_nop 0
	global_load_lds_dwordx4 v136, s[4:5]
	s_waitcnt lgkmcnt(8)
	s_barrier
	s_waitcnt lgkmcnt(7)
	v_mfma_f32_16x16x32_bf16 v[124:127], v[138:141], v[158:161], v[124:127]
	v_mfma_f32_16x16x32_bf16 v[120:123], v[150:153], v[158:161], v[120:123]
	s_waitcnt lgkmcnt(6)
	v_mfma_f32_16x16x32_bf16 v[116:119], v[138:141], v[166:169], v[116:119]
	v_mfma_f32_16x16x32_bf16 v[108:111], v[150:153], v[166:169], v[108:111]
	s_waitcnt lgkmcnt(5)
	v_mfma_f32_16x16x32_bf16 v[100:103], v[138:141], v[188:191], v[100:103]
	v_mfma_f32_16x16x32_bf16 v[92:95], v[150:153], v[188:191], v[92:95]
	s_waitcnt lgkmcnt(4)
	v_mfma_f32_16x16x32_bf16 v[84:87], v[138:141], v[196:199], v[84:87]
	v_mfma_f32_16x16x32_bf16 v[76:79], v[150:153], v[196:199], v[76:79]
	s_waitcnt lgkmcnt(3)
	v_mfma_f32_16x16x32_bf16 v[124:127], v[146:149], v[162:165], v[124:127]
	v_mfma_f32_16x16x32_bf16 v[120:123], v[154:157], v[162:165], v[120:123]
	s_waitcnt lgkmcnt(2)
	v_mfma_f32_16x16x32_bf16 v[116:119], v[146:149], v[170:173], v[116:119]
	v_mfma_f32_16x16x32_bf16 v[108:111], v[154:157], v[170:173], v[108:111]
	s_waitcnt lgkmcnt(1)
	v_mfma_f32_16x16x32_bf16 v[100:103], v[146:149], v[192:195], v[100:103]
	v_mfma_f32_16x16x32_bf16 v[92:95], v[154:157], v[192:195], v[92:95]
	s_waitcnt lgkmcnt(0)
	v_mfma_f32_16x16x32_bf16 v[84:87], v[146:149], v[200:203], v[84:87]
	v_mfma_f32_16x16x32_bf16 v[76:79], v[154:157], v[200:203], v[76:79]
	s_barrier
	s_add_i32 s29, 0, 0x14000
	v_add_u32_e32 v174, s29, v144
	s_add_i32 s28, s28, s77
	ds_read_b128 v[204:207], v174
	ds_read_b128 v[208:211], v174 offset:1024
	ds_read_b128 v[212:215], v174 offset:2048
	ds_read_b128 v[232:235], v174 offset:3072
	s_mov_b32 m0, s28
	s_nop 0
	global_load_lds_dwordx4 v176, s[6:7]
	s_add_i32 m0, s28, 0x2000
	s_nop 0
	global_load_lds_dwordx4 v132, s[6:7]
	s_barrier
	s_waitcnt lgkmcnt(3)
	v_mfma_f32_16x16x32_bf16 v[112:115], v[204:207], v[158:161], v[112:115]
	s_waitcnt lgkmcnt(1)
	v_mfma_f32_16x16x32_bf16 v[104:107], v[212:215], v[158:161], v[104:107]
	v_mfma_f32_16x16x32_bf16 v[96:99], v[204:207], v[166:169], v[96:99]
	v_mfma_f32_16x16x32_bf16 v[88:91], v[212:215], v[166:169], v[88:91]
	v_mfma_f32_16x16x32_bf16 v[80:83], v[204:207], v[188:191], v[80:83]
	v_mfma_f32_16x16x32_bf16 v[72:75], v[212:215], v[188:191], v[72:75]
	v_mfma_f32_16x16x32_bf16 v[68:71], v[204:207], v[196:199], v[68:71]
	v_mfma_f32_16x16x32_bf16 v[64:67], v[212:215], v[196:199], v[64:67]
	v_mfma_f32_16x16x32_bf16 v[112:115], v[208:211], v[162:165], v[112:115]
	s_waitcnt lgkmcnt(0)
	v_mfma_f32_16x16x32_bf16 v[104:107], v[232:235], v[162:165], v[104:107]
	v_mfma_f32_16x16x32_bf16 v[96:99], v[208:211], v[170:173], v[96:99]
	v_mfma_f32_16x16x32_bf16 v[88:91], v[232:235], v[170:173], v[88:91]
	v_mfma_f32_16x16x32_bf16 v[80:83], v[208:211], v[192:195], v[80:83]
	v_mfma_f32_16x16x32_bf16 v[72:75], v[232:235], v[192:195], v[72:75]
	v_mfma_f32_16x16x32_bf16 v[68:71], v[208:211], v[200:203], v[68:71]
	v_mfma_f32_16x16x32_bf16 v[64:67], v[232:235], v[200:203], v[64:67]
	s_mov_b32 m0, s17
	s_barrier
	ds_read_b128 v[158:161], v145 offset:16384
	ds_read_b128 v[166:169], v145 offset:18432
	ds_read_b128 v[188:191], v145 offset:20480
	ds_read_b128 v[196:199], v145 offset:22528
	ds_read_b128 v[162:165], v145 offset:17408
	ds_read_b128 v[170:173], v145 offset:19456
	ds_read_b128 v[192:195], v145 offset:21504
	ds_read_b128 v[200:203], v145 offset:23552
	global_load_lds_dwordx4 v128, s[8:9]
	s_mov_b32 m0, s19
	s_nop 0
	global_load_lds_dwordx4 v130, s[8:9]
	s_barrier
	s_waitcnt lgkmcnt(7)
	v_mfma_f32_16x16x32_bf16 v[60:63], v[138:141], v[158:161], v[60:63]
	v_mfma_f32_16x16x32_bf16 v[56:59], v[150:153], v[158:161], v[56:59]
	s_waitcnt lgkmcnt(6)
	v_mfma_f32_16x16x32_bf16 v[52:55], v[138:141], v[166:169], v[52:55]
	v_mfma_f32_16x16x32_bf16 v[44:47], v[150:153], v[166:169], v[44:47]
	s_waitcnt lgkmcnt(5)
	v_mfma_f32_16x16x32_bf16 v[36:39], v[138:141], v[188:191], v[36:39]
	v_mfma_f32_16x16x32_bf16 v[28:31], v[150:153], v[188:191], v[28:31]
	s_waitcnt lgkmcnt(4)
	v_mfma_f32_16x16x32_bf16 v[20:23], v[138:141], v[196:199], v[20:23]
	v_mfma_f32_16x16x32_bf16 v[12:15], v[150:153], v[196:199], v[12:15]
	s_waitcnt lgkmcnt(3)
	v_mfma_f32_16x16x32_bf16 v[60:63], v[146:149], v[162:165], v[60:63]
	v_mfma_f32_16x16x32_bf16 v[56:59], v[154:157], v[162:165], v[56:59]
	s_waitcnt lgkmcnt(2)
	v_mfma_f32_16x16x32_bf16 v[52:55], v[146:149], v[170:173], v[52:55]
	v_mfma_f32_16x16x32_bf16 v[44:47], v[154:157], v[170:173], v[44:47]
	s_waitcnt lgkmcnt(1)
	v_mfma_f32_16x16x32_bf16 v[36:39], v[146:149], v[192:195], v[36:39]
	v_mfma_f32_16x16x32_bf16 v[28:31], v[154:157], v[192:195], v[28:31]
	s_waitcnt lgkmcnt(0)
	v_mfma_f32_16x16x32_bf16 v[20:23], v[146:149], v[200:203], v[20:23]
	v_mfma_f32_16x16x32_bf16 v[12:15], v[154:157], v[200:203], v[12:15]
	s_barrier
	s_add_u32 vcc_lo, s6, 0x80000
	s_addc_u32 vcc_hi, s7, 0
	s_add_i32 s28, s29, s77
	s_mov_b32 m0, s28
	s_nop 0
	global_load_lds_dwordx4 v176, vcc
	s_add_i32 m0, s28, 0x2000
	s_nop 0
	global_load_lds_dwordx4 v132, vcc
	s_waitcnt vmcnt(6)
	s_barrier
	v_mfma_f32_16x16x32_bf16 v[48:51], v[204:207], v[158:161], v[48:51]
	v_mfma_f32_16x16x32_bf16 v[40:43], v[212:215], v[158:161], v[40:43]
	v_mfma_f32_16x16x32_bf16 v[32:35], v[204:207], v[166:169], v[32:35]
	v_mfma_f32_16x16x32_bf16 v[24:27], v[212:215], v[166:169], v[24:27]
	v_mfma_f32_16x16x32_bf16 v[16:19], v[204:207], v[188:191], v[16:19]
	v_mfma_f32_16x16x32_bf16 v[8:11], v[212:215], v[188:191], v[8:11]
	v_mfma_f32_16x16x32_bf16 v[4:7], v[204:207], v[196:199], v[4:7]
	v_mfma_f32_16x16x32_bf16 v[0:3], v[212:215], v[196:199], v[0:3]
	v_mfma_f32_16x16x32_bf16 v[48:51], v[208:211], v[162:165], v[48:51]
	v_mfma_f32_16x16x32_bf16 v[40:43], v[232:235], v[162:165], v[40:43]
	v_mfma_f32_16x16x32_bf16 v[32:35], v[208:211], v[170:173], v[32:35]
	v_mfma_f32_16x16x32_bf16 v[24:27], v[232:235], v[170:173], v[24:27]
	v_mfma_f32_16x16x32_bf16 v[16:19], v[208:211], v[192:195], v[16:19]
	v_mfma_f32_16x16x32_bf16 v[8:11], v[232:235], v[192:195], v[8:11]
	v_mfma_f32_16x16x32_bf16 v[4:7], v[208:211], v[200:203], v[4:7]
	v_mfma_f32_16x16x32_bf16 v[0:3], v[232:235], v[200:203], v[0:3]
	s_add_i32 s28, 0, 0x18000
	v_add_u32_e32 v154, s28, v144
	s_barrier
	ds_read_b128 v[138:141], v154
	ds_read_b128 v[146:149], v154 offset:1024
	ds_read_b128 v[150:153], v154 offset:2048
	ds_read_b128 v[154:157], v154 offset:3072
	s_add_u32 s98, s8, 0x80000
	s_addc_u32 s99, s9, 0
	s_mov_b32 m0, s78
	ds_read_b128 v[158:161], v145 offset:32768
	ds_read_b128 v[166:169], v145 offset:34816
	ds_read_b128 v[188:191], v145 offset:36864
	ds_read_b128 v[196:199], v145 offset:38912
	ds_read_b128 v[162:165], v145 offset:33792
	ds_read_b128 v[170:173], v145 offset:35840
	ds_read_b128 v[192:195], v145 offset:37888
	ds_read_b128 v[200:203], v145 offset:39936
	global_load_lds_dwordx4 v128, s[98:99]
	s_mov_b32 m0, s79
	s_nop 0
	global_load_lds_dwordx4 v130, s[98:99]
	s_waitcnt lgkmcnt(8)
	s_barrier
	s_waitcnt lgkmcnt(7)
	v_mfma_f32_16x16x32_bf16 v[124:127], v[138:141], v[158:161], v[124:127]
	v_mfma_f32_16x16x32_bf16 v[120:123], v[150:153], v[158:161], v[120:123]
	s_waitcnt lgkmcnt(6)
	v_mfma_f32_16x16x32_bf16 v[116:119], v[138:141], v[166:169], v[116:119]
	v_mfma_f32_16x16x32_bf16 v[108:111], v[150:153], v[166:169], v[108:111]
	s_waitcnt lgkmcnt(5)
	v_mfma_f32_16x16x32_bf16 v[100:103], v[138:141], v[188:191], v[100:103]
	v_mfma_f32_16x16x32_bf16 v[92:95], v[150:153], v[188:191], v[92:95]
	s_waitcnt lgkmcnt(4)
	v_mfma_f32_16x16x32_bf16 v[84:87], v[138:141], v[196:199], v[84:87]
	v_mfma_f32_16x16x32_bf16 v[76:79], v[150:153], v[196:199], v[76:79]
	s_waitcnt lgkmcnt(3)
	v_mfma_f32_16x16x32_bf16 v[124:127], v[146:149], v[162:165], v[124:127]
	v_mfma_f32_16x16x32_bf16 v[120:123], v[154:157], v[162:165], v[120:123]
	s_waitcnt lgkmcnt(2)
	v_mfma_f32_16x16x32_bf16 v[116:119], v[146:149], v[170:173], v[116:119]
	v_mfma_f32_16x16x32_bf16 v[108:111], v[154:157], v[170:173], v[108:111]
	s_waitcnt lgkmcnt(1)
	v_mfma_f32_16x16x32_bf16 v[100:103], v[146:149], v[192:195], v[100:103]
	v_mfma_f32_16x16x32_bf16 v[92:95], v[154:157], v[192:195], v[92:95]
	s_waitcnt lgkmcnt(0)
	v_mfma_f32_16x16x32_bf16 v[84:87], v[146:149], v[200:203], v[84:87]
	v_mfma_f32_16x16x32_bf16 v[76:79], v[154:157], v[200:203], v[76:79]
	s_barrier
	s_add_i32 s100, 0, 0x1c000
	s_add_i32 s101, s28, s77
	v_add_u32_e32 v232, s100, v144
	s_add_i32 m0, s101, 0xffffff80
	ds_read_b128 v[204:207], v232
	ds_read_b128 v[208:211], v232 offset:1024
	ds_read_b128 v[212:215], v232 offset:2048
	ds_read_b128 v[232:235], v232 offset:3072
	global_load_lds_dwordx4 v176, s[6:7] offset:128
	s_add_i32 m0, s101, 0x1f80
	s_nop 0
	global_load_lds_dwordx4 v132, s[6:7] offset:128
	s_barrier
	s_waitcnt lgkmcnt(3)
	v_mfma_f32_16x16x32_bf16 v[112:115], v[204:207], v[158:161], v[112:115]
	s_waitcnt lgkmcnt(1)
	v_mfma_f32_16x16x32_bf16 v[104:107], v[212:215], v[158:161], v[104:107]
	v_mfma_f32_16x16x32_bf16 v[96:99], v[204:207], v[166:169], v[96:99]
	v_mfma_f32_16x16x32_bf16 v[88:91], v[212:215], v[166:169], v[88:91]
	v_mfma_f32_16x16x32_bf16 v[80:83], v[204:207], v[188:191], v[80:83]
	v_mfma_f32_16x16x32_bf16 v[72:75], v[212:215], v[188:191], v[72:75]
	v_mfma_f32_16x16x32_bf16 v[68:71], v[204:207], v[196:199], v[68:71]
	v_mfma_f32_16x16x32_bf16 v[64:67], v[212:215], v[196:199], v[64:67]
	v_mfma_f32_16x16x32_bf16 v[112:115], v[208:211], v[162:165], v[112:115]
	s_waitcnt lgkmcnt(0)
	v_mfma_f32_16x16x32_bf16 v[104:107], v[232:235], v[162:165], v[104:107]
	v_mfma_f32_16x16x32_bf16 v[96:99], v[208:211], v[170:173], v[96:99]
	v_mfma_f32_16x16x32_bf16 v[88:91], v[232:235], v[170:173], v[88:91]
	v_mfma_f32_16x16x32_bf16 v[80:83], v[208:211], v[192:195], v[80:83]
	v_mfma_f32_16x16x32_bf16 v[72:75], v[232:235], v[192:195], v[72:75]
	v_mfma_f32_16x16x32_bf16 v[68:71], v[208:211], v[200:203], v[68:71]
	v_mfma_f32_16x16x32_bf16 v[64:67], v[232:235], v[200:203], v[64:67]
	s_add_i32 m0, s82, 0xffffff80
	s_barrier
	ds_read_b128 v[158:161], v145 offset:49152
	ds_read_b128 v[166:169], v145 offset:51200
	ds_read_b128 v[188:191], v145 offset:53248
	ds_read_b128 v[196:199], v145 offset:55296
	ds_read_b128 v[162:165], v145 offset:50176
	ds_read_b128 v[170:173], v145 offset:52224
	ds_read_b128 v[192:195], v145 offset:54272
	ds_read_b128 v[200:203], v145 offset:56320
	global_load_lds_dwordx4 v128, s[8:9] offset:128
	s_add_i32 m0, s83, 0xffffff80
	s_nop 0
	global_load_lds_dwordx4 v130, s[8:9] offset:128
	s_barrier
	s_waitcnt lgkmcnt(7)
	v_mfma_f32_16x16x32_bf16 v[60:63], v[138:141], v[158:161], v[60:63]
	v_mfma_f32_16x16x32_bf16 v[56:59], v[150:153], v[158:161], v[56:59]
	s_waitcnt lgkmcnt(6)
	v_mfma_f32_16x16x32_bf16 v[52:55], v[138:141], v[166:169], v[52:55]
	v_mfma_f32_16x16x32_bf16 v[44:47], v[150:153], v[166:169], v[44:47]
	s_waitcnt lgkmcnt(5)
	v_mfma_f32_16x16x32_bf16 v[36:39], v[138:141], v[188:191], v[36:39]
	v_mfma_f32_16x16x32_bf16 v[28:31], v[150:153], v[188:191], v[28:31]
	s_waitcnt lgkmcnt(4)
	v_mfma_f32_16x16x32_bf16 v[20:23], v[138:141], v[196:199], v[20:23]
	v_mfma_f32_16x16x32_bf16 v[12:15], v[150:153], v[196:199], v[12:15]
	s_waitcnt lgkmcnt(3)
	v_mfma_f32_16x16x32_bf16 v[60:63], v[146:149], v[162:165], v[60:63]
	v_mfma_f32_16x16x32_bf16 v[56:59], v[154:157], v[162:165], v[56:59]
	s_waitcnt lgkmcnt(2)
	v_mfma_f32_16x16x32_bf16 v[52:55], v[146:149], v[170:173], v[52:55]
	v_mfma_f32_16x16x32_bf16 v[44:47], v[154:157], v[170:173], v[44:47]
	s_waitcnt lgkmcnt(1)
	v_mfma_f32_16x16x32_bf16 v[36:39], v[146:149], v[192:195], v[36:39]
	v_mfma_f32_16x16x32_bf16 v[28:31], v[154:157], v[192:195], v[28:31]
	s_waitcnt lgkmcnt(0)
	v_mfma_f32_16x16x32_bf16 v[20:23], v[146:149], v[200:203], v[20:23]
	v_mfma_f32_16x16x32_bf16 v[12:15], v[154:157], v[200:203], v[12:15]
	s_barrier
	s_add_u32 s6, s6, 0x80080
	s_addc_u32 s7, s7, 0
	s_add_i32 s100, s100, s77
	s_mov_b32 m0, s100
	s_nop 0
	global_load_lds_dwordx4 v176, s[6:7]
	s_add_i32 m0, s100, 0x2000
	s_nop 0
	global_load_lds_dwordx4 v132, s[6:7]
	s_waitcnt vmcnt(6)
	s_barrier
	v_mfma_f32_16x16x32_bf16 v[48:51], v[204:207], v[158:161], v[48:51]
	v_mfma_f32_16x16x32_bf16 v[40:43], v[212:215], v[158:161], v[40:43]
	v_mfma_f32_16x16x32_bf16 v[32:35], v[204:207], v[166:169], v[32:35]
	v_mfma_f32_16x16x32_bf16 v[24:27], v[212:215], v[166:169], v[24:27]
	v_mfma_f32_16x16x32_bf16 v[16:19], v[204:207], v[188:191], v[16:19]
	v_mfma_f32_16x16x32_bf16 v[8:11], v[212:215], v[188:191], v[8:11]
	v_mfma_f32_16x16x32_bf16 v[4:7], v[204:207], v[196:199], v[4:7]
	v_mfma_f32_16x16x32_bf16 v[0:3], v[212:215], v[196:199], v[0:3]
	v_mfma_f32_16x16x32_bf16 v[48:51], v[208:211], v[162:165], v[48:51]
	v_mfma_f32_16x16x32_bf16 v[40:43], v[232:235], v[162:165], v[40:43]
	v_mfma_f32_16x16x32_bf16 v[32:35], v[208:211], v[170:173], v[32:35]
	v_mfma_f32_16x16x32_bf16 v[24:27], v[232:235], v[170:173], v[24:27]
	v_mfma_f32_16x16x32_bf16 v[16:19], v[208:211], v[192:195], v[16:19]
	v_mfma_f32_16x16x32_bf16 v[8:11], v[232:235], v[192:195], v[8:11]
	v_mfma_f32_16x16x32_bf16 v[4:7], v[208:211], v[200:203], v[4:7]
	v_mfma_f32_16x16x32_bf16 v[0:3], v[232:235], v[200:203], v[0:3]
	s_add_i32 s72, s72, 2
	s_add_u32 s4, s4, 0x100
	s_addc_u32 s5, s5, 0
	s_add_u32 s70, s70, 0x100
	s_addc_u32 s71, s71, 0
	s_cmp_lt_u32 s72, 30
	s_barrier
	s_cbranch_scc1 .LBB0_505
	v_mov_b32_e32 v147, v142
	v_mov_b32_e32 v146, v143
	s_cmp_lt_i32 s16, 12
	s_mov_b64 s[4:5], -1
	s_cbranch_scc1 .LBB0_1052
	s_lshl_b32 s4, s18, 8
	s_add_i32 s4, s4, s80
	v_add_u32_e32 v149, s4, v147
	s_lshl_b32 s4, s16, 8
	s_add_i32 s4, s84, s4
	v_lshl_add_u32 v138, v146, 3, s4
	v_mad_i64_i32 v[140:141], s[4:5], v149, s97, 0
	v_cmp_gt_i32_e32 vcc, s34, v138
	s_and_saveexec_b64 s[10:11], vcc
	s_cbranch_execz .LBB0_541
	v_cmp_lt_i32_e64 s[8:9], 63, v138
	v_cmp_gt_u32_e64 s[4:5], s93, v138
	v_cmp_gt_u32_e64 s[6:7], s96, v138
	s_and_saveexec_b64 s[70:71], s[8:9]
	s_xor_b64 s[70:71], exec, s[70:71]
	s_cbranch_execz .LBB0_510
	v_mul_f32_e32 v139, 0xbfb8aa3b, v124
	v_exp_f32_e32 v139, v139
	s_nop 0
	v_add_f32_e32 v139, 1.0, v139
	v_rcp_f32_e32 v139, v139
	s_nop 0
	v_cndmask_b32_e64 v139, 0, v139, s[6:7]
	v_cndmask_b32_e64 v139, v139, v124, s[4:5]
	s_andn2_saveexec_b64 s[70:71], s[70:71]
	s_cbranch_execz .LBB0_512
	s_branch .LBB0_511

.LBB0_1114:
	s_add_i32 vcc_hi, s66, 2
	s_add_u32 s28, s64, 0x80
	s_addc_u32 s29, s65, 0
	s_add_i32 s88, 0, 0x10000
	v_add_u32_e32 v140, s88, v194
	ds_read_b128 v[128:131], v140
	ds_read_b128 v[132:135], v140 offset:1024
	ds_read_b128 v[136:139], v140 offset:2048
	ds_read_b128 v[140:143], v140 offset:3072
	s_cmp_eq_u32 s85, s66
	s_cselect_b32 s66, s4, s28
	s_cselect_b32 s67, s5, s29
	s_cselect_b32 s69, s7, vcc_lo
	s_cselect_b32 s68, s6, s91
	s_add_i32 m0, s70, 0xc000
	ds_read_b128 v[144:147], v195
	ds_read_b128 v[162:165], v195 offset:2048
	ds_read_b128 v[170:173], v195 offset:4096
	ds_read_b128 v[196:199], v195 offset:6144
	ds_read_b128 v[148:151], v195 offset:1024
	ds_read_b128 v[166:169], v195 offset:3072
	ds_read_b128 v[188:191], v195 offset:5120
	ds_read_b128 v[200:203], v195 offset:7168
	global_load_lds_dwordx4 v158, s[64:65]
	s_add_i32 m0, s70, 0xe000
	s_nop 0
	global_load_lds_dwordx4 v160, s[64:65]
	s_waitcnt lgkmcnt(8)
	s_barrier
	s_waitcnt lgkmcnt(7)
	v_mfma_f32_16x16x32_bf16 v[124:127], v[128:131], v[144:147], v[124:127]
	v_mfma_f32_16x16x32_bf16 v[120:123], v[136:139], v[144:147], v[120:123]
	s_waitcnt lgkmcnt(6)
	v_mfma_f32_16x16x32_bf16 v[108:111], v[128:131], v[162:165], v[108:111]
	v_mfma_f32_16x16x32_bf16 v[104:107], v[136:139], v[162:165], v[104:107]
	s_waitcnt lgkmcnt(5)
	v_mfma_f32_16x16x32_bf16 v[92:95], v[128:131], v[170:173], v[92:95]
	v_mfma_f32_16x16x32_bf16 v[88:91], v[136:139], v[170:173], v[88:91]
	s_waitcnt lgkmcnt(4)
	v_mfma_f32_16x16x32_bf16 v[76:79], v[128:131], v[196:199], v[76:79]
	v_mfma_f32_16x16x32_bf16 v[72:75], v[136:139], v[196:199], v[72:75]
	s_waitcnt lgkmcnt(3)
	v_mfma_f32_16x16x32_bf16 v[124:127], v[132:135], v[148:151], v[124:127]
	v_mfma_f32_16x16x32_bf16 v[120:123], v[140:143], v[148:151], v[120:123]
	s_waitcnt lgkmcnt(2)
	v_mfma_f32_16x16x32_bf16 v[108:111], v[132:135], v[166:169], v[108:111]
	v_mfma_f32_16x16x32_bf16 v[104:107], v[140:143], v[166:169], v[104:107]
	s_waitcnt lgkmcnt(1)
	v_mfma_f32_16x16x32_bf16 v[92:95], v[132:135], v[188:191], v[92:95]
	v_mfma_f32_16x16x32_bf16 v[88:91], v[140:143], v[188:191], v[88:91]
	s_waitcnt lgkmcnt(0)
	v_mfma_f32_16x16x32_bf16 v[76:79], v[132:135], v[200:203], v[76:79]
	v_mfma_f32_16x16x32_bf16 v[72:75], v[140:143], v[200:203], v[72:75]
	s_barrier
	s_add_i32 s28, 0, 0x14000
	v_add_u32_e32 v174, s28, v194
	s_add_i32 s29, s88, s47
	ds_read_b128 v[204:207], v174
	ds_read_b128 v[208:211], v174 offset:1024
	ds_read_b128 v[212:215], v174 offset:2048
	ds_read_b128 v[232:235], v174 offset:3072
	s_mov_b32 m0, s29
	s_nop 0
	global_load_lds_dwordx4 v176, s[68:69]
	s_add_i32 m0, s29, 0x2000
	s_nop 0
	global_load_lds_dwordx4 v156, s[68:69]
	s_barrier
	s_waitcnt lgkmcnt(3)
	v_mfma_f32_16x16x32_bf16 v[116:119], v[204:207], v[144:147], v[116:119]
	s_waitcnt lgkmcnt(1)
	v_mfma_f32_16x16x32_bf16 v[112:115], v[212:215], v[144:147], v[112:115]
	v_mfma_f32_16x16x32_bf16 v[100:103], v[204:207], v[162:165], v[100:103]
	v_mfma_f32_16x16x32_bf16 v[96:99], v[212:215], v[162:165], v[96:99]
	v_mfma_f32_16x16x32_bf16 v[84:87], v[204:207], v[170:173], v[84:87]
	v_mfma_f32_16x16x32_bf16 v[80:83], v[212:215], v[170:173], v[80:83]
	v_mfma_f32_16x16x32_bf16 v[68:71], v[204:207], v[196:199], v[68:71]
	v_mfma_f32_16x16x32_bf16 v[64:67], v[212:215], v[196:199], v[64:67]
	v_mfma_f32_16x16x32_bf16 v[116:119], v[208:211], v[148:151], v[116:119]
	s_waitcnt lgkmcnt(0)
	v_mfma_f32_16x16x32_bf16 v[112:115], v[232:235], v[148:151], v[112:115]
	v_mfma_f32_16x16x32_bf16 v[100:103], v[208:211], v[166:169], v[100:103]
	v_mfma_f32_16x16x32_bf16 v[96:99], v[232:235], v[166:169], v[96:99]
	v_mfma_f32_16x16x32_bf16 v[84:87], v[208:211], v[188:191], v[84:87]
	v_mfma_f32_16x16x32_bf16 v[80:83], v[232:235], v[188:191], v[80:83]
	v_mfma_f32_16x16x32_bf16 v[68:71], v[208:211], v[200:203], v[68:71]
	v_mfma_f32_16x16x32_bf16 v[64:67], v[232:235], v[200:203], v[64:67]
	s_mov_b32 m0, s70
	s_barrier
	ds_read_b128 v[144:147], v195 offset:16384
	ds_read_b128 v[162:165], v195 offset:18432
	ds_read_b128 v[170:173], v195 offset:20480
	ds_read_b128 v[196:199], v195 offset:22528
	ds_read_b128 v[148:151], v195 offset:17408
	ds_read_b128 v[166:169], v195 offset:19456
	ds_read_b128 v[188:191], v195 offset:21504
	ds_read_b128 v[200:203], v195 offset:23552
	global_load_lds_dwordx4 v152, s[66:67]
	s_mov_b32 m0, s71
	s_nop 0
	global_load_lds_dwordx4 v154, s[66:67]
	s_barrier
	s_waitcnt lgkmcnt(7)
	v_mfma_f32_16x16x32_bf16 v[60:63], v[128:131], v[144:147], v[60:63]
	v_mfma_f32_16x16x32_bf16 v[56:59], v[136:139], v[144:147], v[56:59]
	s_waitcnt lgkmcnt(6)
	v_mfma_f32_16x16x32_bf16 v[44:47], v[128:131], v[162:165], v[44:47]
	v_mfma_f32_16x16x32_bf16 v[40:43], v[136:139], v[162:165], v[40:43]
	s_waitcnt lgkmcnt(5)
	v_mfma_f32_16x16x32_bf16 v[28:31], v[128:131], v[170:173], v[28:31]
	v_mfma_f32_16x16x32_bf16 v[24:27], v[136:139], v[170:173], v[24:27]
	s_waitcnt lgkmcnt(4)
	v_mfma_f32_16x16x32_bf16 v[12:15], v[128:131], v[196:199], v[12:15]
	v_mfma_f32_16x16x32_bf16 v[8:11], v[136:139], v[196:199], v[8:11]
	s_waitcnt lgkmcnt(3)
	v_mfma_f32_16x16x32_bf16 v[60:63], v[132:135], v[148:151], v[60:63]
	v_mfma_f32_16x16x32_bf16 v[56:59], v[140:143], v[148:151], v[56:59]
	s_waitcnt lgkmcnt(2)
	v_mfma_f32_16x16x32_bf16 v[44:47], v[132:135], v[166:169], v[44:47]
	v_mfma_f32_16x16x32_bf16 v[40:43], v[140:143], v[166:169], v[40:43]
	s_waitcnt lgkmcnt(1)
	v_mfma_f32_16x16x32_bf16 v[28:31], v[132:135], v[188:191], v[28:31]
	v_mfma_f32_16x16x32_bf16 v[24:27], v[140:143], v[188:191], v[24:27]
	s_waitcnt lgkmcnt(0)
	v_mfma_f32_16x16x32_bf16 v[12:15], v[132:135], v[200:203], v[12:15]
	v_mfma_f32_16x16x32_bf16 v[8:11], v[140:143], v[200:203], v[8:11]
	s_barrier
	s_add_u32 s98, s68, s58
	s_addc_u32 s99, s69, 0
	s_add_i32 s28, s28, s47
	s_mov_b32 m0, s28
	s_nop 0
	global_load_lds_dwordx4 v176, s[98:99]
	s_add_i32 m0, s28, 0x2000
	s_nop 0
	global_load_lds_dwordx4 v156, s[98:99]
	s_waitcnt vmcnt(6)
	s_barrier
	v_mfma_f32_16x16x32_bf16 v[52:55], v[204:207], v[144:147], v[52:55]
	v_mfma_f32_16x16x32_bf16 v[48:51], v[212:215], v[144:147], v[48:51]
	v_mfma_f32_16x16x32_bf16 v[36:39], v[204:207], v[162:165], v[36:39]
	v_mfma_f32_16x16x32_bf16 v[32:35], v[212:215], v[162:165], v[32:35]
	v_mfma_f32_16x16x32_bf16 v[20:23], v[204:207], v[170:173], v[20:23]
	v_mfma_f32_16x16x32_bf16 v[16:19], v[212:215], v[170:173], v[16:19]
	v_mfma_f32_16x16x32_bf16 v[4:7], v[204:207], v[196:199], v[4:7]
	v_mfma_f32_16x16x32_bf16 v[0:3], v[212:215], v[196:199], v[0:3]
	v_mfma_f32_16x16x32_bf16 v[52:55], v[208:211], v[148:151], v[52:55]
	v_mfma_f32_16x16x32_bf16 v[48:51], v[232:235], v[148:151], v[48:51]
	v_mfma_f32_16x16x32_bf16 v[36:39], v[208:211], v[166:169], v[36:39]
	v_mfma_f32_16x16x32_bf16 v[32:35], v[232:235], v[166:169], v[32:35]
	v_mfma_f32_16x16x32_bf16 v[20:23], v[208:211], v[188:191], v[20:23]
	v_mfma_f32_16x16x32_bf16 v[16:19], v[232:235], v[188:191], v[16:19]
	v_mfma_f32_16x16x32_bf16 v[4:7], v[208:211], v[200:203], v[4:7]
	v_mfma_f32_16x16x32_bf16 v[0:3], v[232:235], v[200:203], v[0:3]
	s_add_i32 s28, 0, 0x18000
	v_add_u32_e32 v140, s28, v194
	s_barrier
	ds_read_b128 v[128:131], v140
	ds_read_b128 v[132:135], v140 offset:1024
	ds_read_b128 v[136:139], v140 offset:2048
	ds_read_b128 v[140:143], v140 offset:3072
	s_add_u32 s100, s66, s58
	s_addc_u32 s101, s67, 0
	s_mov_b32 m0, s72
	ds_read_b128 v[144:147], v195 offset:32768
	ds_read_b128 v[162:165], v195 offset:34816
	ds_read_b128 v[170:173], v195 offset:36864
	ds_read_b128 v[196:199], v195 offset:38912
	ds_read_b128 v[148:151], v195 offset:33792
	ds_read_b128 v[166:169], v195 offset:35840
	ds_read_b128 v[188:191], v195 offset:37888
	ds_read_b128 v[200:203], v195 offset:39936
	global_load_lds_dwordx4 v152, s[100:101]
	s_mov_b32 m0, s73
	s_nop 0
	global_load_lds_dwordx4 v154, s[100:101]
	s_waitcnt lgkmcnt(8)
	s_barrier
	s_waitcnt lgkmcnt(7)
	v_mfma_f32_16x16x32_bf16 v[124:127], v[128:131], v[144:147], v[124:127]
	v_mfma_f32_16x16x32_bf16 v[120:123], v[136:139], v[144:147], v[120:123]
	s_waitcnt lgkmcnt(6)
	v_mfma_f32_16x16x32_bf16 v[108:111], v[128:131], v[162:165], v[108:111]
	v_mfma_f32_16x16x32_bf16 v[104:107], v[136:139], v[162:165], v[104:107]
	s_waitcnt lgkmcnt(5)
	v_mfma_f32_16x16x32_bf16 v[92:95], v[128:131], v[170:173], v[92:95]
	v_mfma_f32_16x16x32_bf16 v[88:91], v[136:139], v[170:173], v[88:91]
	s_waitcnt lgkmcnt(4)
	v_mfma_f32_16x16x32_bf16 v[76:79], v[128:131], v[196:199], v[76:79]
	v_mfma_f32_16x16x32_bf16 v[72:75], v[136:139], v[196:199], v[72:75]
	s_waitcnt lgkmcnt(3)
	v_mfma_f32_16x16x32_bf16 v[124:127], v[132:135], v[148:151], v[124:127]
	v_mfma_f32_16x16x32_bf16 v[120:123], v[140:143], v[148:151], v[120:123]
	s_waitcnt lgkmcnt(2)
	v_mfma_f32_16x16x32_bf16 v[108:111], v[132:135], v[166:169], v[108:111]
	v_mfma_f32_16x16x32_bf16 v[104:107], v[140:143], v[166:169], v[104:107]
	s_waitcnt lgkmcnt(1)
	v_mfma_f32_16x16x32_bf16 v[92:95], v[132:135], v[188:191], v[92:95]
	v_mfma_f32_16x16x32_bf16 v[88:91], v[140:143], v[188:191], v[88:91]
	s_waitcnt lgkmcnt(0)
	v_mfma_f32_16x16x32_bf16 v[76:79], v[132:135], v[200:203], v[76:79]
	v_mfma_f32_16x16x32_bf16 v[72:75], v[140:143], v[200:203], v[72:75]
	s_barrier
	s_add_i32 s29, 0, 0x1c000
	s_add_i32 s28, s28, s47
	v_add_u32_e32 v232, s29, v194
	s_add_i32 m0, s28, 0xffffff80
	ds_read_b128 v[204:207], v232
	ds_read_b128 v[208:211], v232 offset:1024
	ds_read_b128 v[212:215], v232 offset:2048
	ds_read_b128 v[232:235], v232 offset:3072
	global_load_lds_dwordx4 v176, s[68:69] offset:128
	s_add_i32 m0, s28, 0x1f80
	s_nop 0
	global_load_lds_dwordx4 v156, s[68:69] offset:128
	s_barrier
	s_waitcnt lgkmcnt(3)
	v_mfma_f32_16x16x32_bf16 v[116:119], v[204:207], v[144:147], v[116:119]
	s_waitcnt lgkmcnt(1)
	v_mfma_f32_16x16x32_bf16 v[112:115], v[212:215], v[144:147], v[112:115]
	v_mfma_f32_16x16x32_bf16 v[100:103], v[204:207], v[162:165], v[100:103]
	v_mfma_f32_16x16x32_bf16 v[96:99], v[212:215], v[162:165], v[96:99]
	v_mfma_f32_16x16x32_bf16 v[84:87], v[204:207], v[170:173], v[84:87]
	v_mfma_f32_16x16x32_bf16 v[80:83], v[212:215], v[170:173], v[80:83]
	v_mfma_f32_16x16x32_bf16 v[68:71], v[204:207], v[196:199], v[68:71]
	v_mfma_f32_16x16x32_bf16 v[64:67], v[212:215], v[196:199], v[64:67]
	v_mfma_f32_16x16x32_bf16 v[116:119], v[208:211], v[148:151], v[116:119]
	s_waitcnt lgkmcnt(0)
	v_mfma_f32_16x16x32_bf16 v[112:115], v[232:235], v[148:151], v[112:115]
	v_mfma_f32_16x16x32_bf16 v[100:103], v[208:211], v[166:169], v[100:103]
	v_mfma_f32_16x16x32_bf16 v[96:99], v[232:235], v[166:169], v[96:99]
	v_mfma_f32_16x16x32_bf16 v[84:87], v[208:211], v[188:191], v[84:87]
	v_mfma_f32_16x16x32_bf16 v[80:83], v[232:235], v[188:191], v[80:83]
	v_mfma_f32_16x16x32_bf16 v[68:71], v[208:211], v[200:203], v[68:71]
	v_mfma_f32_16x16x32_bf16 v[64:67], v[232:235], v[200:203], v[64:67]
	s_add_i32 m0, s74, 0xffffff80
	s_barrier
	ds_read_b128 v[144:147], v195 offset:49152
	ds_read_b128 v[162:165], v195 offset:51200
	ds_read_b128 v[170:173], v195 offset:53248
	ds_read_b128 v[196:199], v195 offset:55296
	ds_read_b128 v[148:151], v195 offset:50176
	ds_read_b128 v[166:169], v195 offset:52224
	ds_read_b128 v[188:191], v195 offset:54272
	ds_read_b128 v[200:203], v195 offset:56320
	global_load_lds_dwordx4 v152, s[66:67] offset:128
	s_add_i32 m0, s75, 0xffffff80
	s_nop 0
	global_load_lds_dwordx4 v154, s[66:67] offset:128
	s_barrier
	s_waitcnt lgkmcnt(7)
	v_mfma_f32_16x16x32_bf16 v[60:63], v[128:131], v[144:147], v[60:63]
	v_mfma_f32_16x16x32_bf16 v[56:59], v[136:139], v[144:147], v[56:59]
	s_waitcnt lgkmcnt(6)
	v_mfma_f32_16x16x32_bf16 v[44:47], v[128:131], v[162:165], v[44:47]
	v_mfma_f32_16x16x32_bf16 v[40:43], v[136:139], v[162:165], v[40:43]
	s_waitcnt lgkmcnt(5)
	v_mfma_f32_16x16x32_bf16 v[28:31], v[128:131], v[170:173], v[28:31]
	v_mfma_f32_16x16x32_bf16 v[24:27], v[136:139], v[170:173], v[24:27]
	s_waitcnt lgkmcnt(4)
	v_mfma_f32_16x16x32_bf16 v[12:15], v[128:131], v[196:199], v[12:15]
	v_mfma_f32_16x16x32_bf16 v[8:11], v[136:139], v[196:199], v[8:11]
	s_waitcnt lgkmcnt(3)
	v_mfma_f32_16x16x32_bf16 v[60:63], v[132:135], v[148:151], v[60:63]
	v_mfma_f32_16x16x32_bf16 v[56:59], v[140:143], v[148:151], v[56:59]
	s_waitcnt lgkmcnt(2)
	v_mfma_f32_16x16x32_bf16 v[44:47], v[132:135], v[166:169], v[44:47]
	v_mfma_f32_16x16x32_bf16 v[40:43], v[140:143], v[166:169], v[40:43]
	s_waitcnt lgkmcnt(1)
	v_mfma_f32_16x16x32_bf16 v[28:31], v[132:135], v[188:191], v[28:31]
	v_mfma_f32_16x16x32_bf16 v[24:27], v[140:143], v[188:191], v[24:27]
	s_waitcnt lgkmcnt(0)
	v_mfma_f32_16x16x32_bf16 v[12:15], v[132:135], v[200:203], v[12:15]
	v_mfma_f32_16x16x32_bf16 v[8:11], v[140:143], v[200:203], v[8:11]
	s_barrier
	s_add_i32 s28, s29, s47
	s_add_i32 m0, s28, 0xffffff80
	s_nop 0
	global_load_lds_dwordx4 v176, s[98:99] offset:128
	s_add_i32 m0, s28, 0x1f80
	s_nop 0
	global_load_lds_dwordx4 v156, s[98:99] offset:128
	s_waitcnt vmcnt(6)
	s_barrier
	v_mfma_f32_16x16x32_bf16 v[52:55], v[204:207], v[144:147], v[52:55]
	v_mfma_f32_16x16x32_bf16 v[48:51], v[212:215], v[144:147], v[48:51]
	v_mfma_f32_16x16x32_bf16 v[36:39], v[204:207], v[162:165], v[36:39]
	v_mfma_f32_16x16x32_bf16 v[32:35], v[212:215], v[162:165], v[32:35]
	v_mfma_f32_16x16x32_bf16 v[20:23], v[204:207], v[170:173], v[20:23]
	v_mfma_f32_16x16x32_bf16 v[16:19], v[212:215], v[170:173], v[16:19]
	v_mfma_f32_16x16x32_bf16 v[4:7], v[204:207], v[196:199], v[4:7]
	v_mfma_f32_16x16x32_bf16 v[0:3], v[212:215], v[196:199], v[0:3]
	v_mfma_f32_16x16x32_bf16 v[52:55], v[208:211], v[148:151], v[52:55]
	v_mfma_f32_16x16x32_bf16 v[48:51], v[232:235], v[148:151], v[48:51]
	v_mfma_f32_16x16x32_bf16 v[36:39], v[208:211], v[166:169], v[36:39]
	v_mfma_f32_16x16x32_bf16 v[32:35], v[232:235], v[166:169], v[32:35]
	v_mfma_f32_16x16x32_bf16 v[20:23], v[208:211], v[188:191], v[20:23]
	v_mfma_f32_16x16x32_bf16 v[16:19], v[232:235], v[188:191], v[16:19]
	v_mfma_f32_16x16x32_bf16 v[4:7], v[208:211], v[200:203], v[4:7]
	v_mfma_f32_16x16x32_bf16 v[0:3], v[232:235], v[200:203], v[0:3]
	s_add_u32 s64, s64, 0x100
	s_addc_u32 s65, s65, 0
	s_add_u32 s91, s91, 0x100
	s_addc_u32 vcc_lo, vcc_lo, 0
	s_cmp_lt_i32 vcc_hi, s76
	s_mov_b32 s66, vcc_hi
	s_barrier
	s_cbranch_scc1 .LBB0_1114
	s_lshl_b32 s28, s84, 8
	v_mov_b32_e32 v128, v193
	v_mov_b32_e32 v129, v192
	s_add_i32 s28, s28, s78
	s_lshl_b32 s64, s24, 2
	v_add_u32_e32 v166, s28, v129
	s_lshl_b32 s28, s24, 8
	s_or_b32 s28, s28, s79
	v_lshl_add_u32 v162, v128, 3, s28
	v_ashrrev_i32_e32 v163, 31, v162
	v_lshlrev_b64 v[204:205], 1, v[162:163]
	v_ashrrev_i32_e32 v167, 31, v166
	v_lshl_add_u64 v[164:165], s[12:13], 0, v[204:205]
	v_lshlrev_b64 v[206:207], 11, v[166:167]
	v_cmp_eq_u32_e32 vcc, 0, v128
	v_lshl_add_u64 v[128:129], v[164:165], 0, v[206:207]
	global_load_dwordx4 v[196:199], v[128:129], off
	global_load_dwordx4 v[200:203], v[128:129], off offset:256
	v_add_u32_e32 v188, 16, v166
	v_ashrrev_i32_e32 v189, 31, v188
	v_add_u32_e32 v172, 32, v166
	v_lshlrev_b64 v[190:191], 11, v[188:189]
	v_ashrrev_i32_e32 v173, 31, v172
	v_add_u32_e32 v168, 48, v166
	v_lshl_add_u64 v[128:129], v[164:165], 0, v[190:191]
	v_lshlrev_b64 v[174:175], 11, v[172:173]
	v_ashrrev_i32_e32 v169, 31, v168
	global_load_dwordx4 v[148:151], v[128:129], off
	global_load_dwordx4 v[144:147], v[128:129], off offset:256
	v_lshl_add_u64 v[128:129], v[164:165], 0, v[174:175]
	v_lshlrev_b64 v[170:171], 11, v[168:169]
	global_load_dwordx4 v[140:143], v[128:129], off
	global_load_dwordx4 v[136:139], v[128:129], off offset:256
	v_lshl_add_u64 v[128:129], v[164:165], 0, v[170:171]
	global_load_dwordx4 v[132:135], v[128:129], off
	s_nop 0
	global_load_dwordx4 v[128:131], v[128:129], off offset:256
	v_lshl_add_u64 v[206:207], s[12:13], 0, v[206:207]
	v_lshl_add_u64 v[204:205], v[206:207], 0, v[204:205]
	s_ashr_i32 s65, s64, 31
	s_waitcnt vmcnt(0)
	v_lshlrev_b32_e32 v208, 16, v196
	v_and_b32_e32 v209, 0xffff0000, v196
	v_lshlrev_b32_e32 v196, 16, v197
	v_and_b32_e32 v197, 0xffff0000, v197
	v_lshlrev_b32_e32 v210, 16, v198
	v_and_b32_e32 v211, 0xffff0000, v198
	v_lshlrev_b32_e32 v198, 16, v199
	v_and_b32_e32 v199, 0xffff0000, v199
	v_pk_fma_f32 v[126:127], s[62:63], v[126:127], v[196:197]
	v_pk_fma_f32 v[124:125], s[10:11], v[124:125], v[208:209]
	v_pk_fma_f32 v[196:197], s[62:63], v[122:123], v[198:199]
	v_pk_fma_f32 v[198:199], s[10:11], v[120:121], v[210:211]
	v_cvt_pk_bf16_f32 v120, v124, v125
	v_cvt_pk_bf16_f32 v121, v126, v127
	s_nop 0
	v_cvt_pk_bf16_f32 v122, v198, v199
	v_cvt_pk_bf16_f32 v123, v196, v197
	global_store_dwordx4 v[204:205], v[120:123], off
	s_nop 1
	v_pk_mul_f32 v[120:121], v[198:199], v[198:199]
	v_pk_mul_f32 v[122:123], v[196:197], v[196:197]
	v_pk_fma_f32 v[120:121], v[124:125], v[124:125], v[120:121]
	v_pk_fma_f32 v[122:123], v[126:127], v[126:127], v[122:123]
	v_add_f32_e32 v120, v120, v121
	v_add_f32_e32 v121, v122, v123
	v_add_f32_e32 v196, v120, v121
	v_lshlrev_b32_e32 v120, 16, v200
	v_and_b32_e32 v121, 0xffff0000, v200
	v_lshlrev_b32_e32 v122, 16, v201
	v_and_b32_e32 v123, 0xffff0000, v201
	v_lshlrev_b32_e32 v124, 16, v202
	v_and_b32_e32 v125, 0xffff0000, v202
	v_lshlrev_b32_e32 v126, 16, v203
	v_and_b32_e32 v127, 0xffff0000, v203
	v_pk_fma_f32 v[118:119], s[62:63], v[118:119], v[122:123]
	v_pk_fma_f32 v[116:117], s[10:11], v[116:117], v[120:121]
	v_pk_fma_f32 v[120:121], s[62:63], v[114:115], v[126:127]
	v_pk_fma_f32 v[122:123], s[10:11], v[112:113], v[124:125]
	v_cvt_pk_bf16_f32 v112, v116, v117
	v_cvt_pk_bf16_f32 v113, v118, v119
	s_nop 0
	v_cvt_pk_bf16_f32 v114, v122, v123
	v_cvt_pk_bf16_f32 v115, v120, v121
	global_store_dwordx4 v[204:205], v[112:115], off offset:256
	s_nop 1
	v_pk_mul_f32 v[112:113], v[122:123], v[122:123]
	v_pk_mul_f32 v[114:115], v[120:121], v[120:121]
	v_pk_fma_f32 v[112:113], v[116:117], v[116:117], v[112:113]
	v_pk_fma_f32 v[114:115], v[118:119], v[118:119], v[114:115]
	v_add_f32_e32 v112, v112, v113
	v_add_f32_e32 v113, v114, v115
	v_add_f32_e32 v112, v112, v113
	v_add_f32_e32 v112, v196, v112
	ds_bpermute_b32 v113, v219, v112
	s_waitcnt lgkmcnt(0)
	v_add_f32_e32 v112, v112, v113
	ds_bpermute_b32 v113, v218, v112
	s_and_saveexec_b64 s[66:67], vcc
	s_cbranch_execz .LBB0_1117
	v_lshlrev_b64 v[114:115], 6, v[166:167]
	v_lshl_add_u64 v[114:115], s[8:9], 0, v[114:115]
	v_lshl_add_u64 v[114:115], s[64:65], 2, v[114:115]
	s_lshl_b32 s24, s77, 2
	v_lshl_add_u64 v[114:115], v[114:115], 0, s[24:25]
	s_waitcnt lgkmcnt(0)
	v_add_f32_e32 v112, v112, v113
	global_store_dword v[114:115], v112, off

.LBB0_1282:
	s_add_i32 s81, s60, 2
	s_add_u32 s28, s58, 0x80
	s_addc_u32 s29, s59, 0
	s_add_i32 s82, 0, 0x10000
	v_add_u32_e32 v140, s82, v195
	ds_read_b128 v[128:131], v140
	ds_read_b128 v[132:135], v140 offset:1024
	ds_read_b128 v[136:139], v140 offset:2048
	ds_read_b128 v[140:143], v140 offset:3072
	s_cmp_eq_u32 s5, s60
	s_cselect_b32 s60, s56, s28
	s_cselect_b32 s61, s57, s29
	s_cselect_b32 s63, s3, s80
	s_cselect_b32 s62, s2, s21
	s_add_i32 m0, s66, 0xc000
	ds_read_b128 v[144:147], v196
	ds_read_b128 v[162:165], v196 offset:2048
	ds_read_b128 v[170:173], v196 offset:4096
	ds_read_b128 v[198:201], v196 offset:6144
	ds_read_b128 v[148:151], v196 offset:1024
	ds_read_b128 v[166:169], v196 offset:3072
	ds_read_b128 v[188:191], v196 offset:5120
	ds_read_b128 v[202:205], v196 offset:7168
	global_load_lds_dwordx4 v158, s[58:59]
	s_add_i32 m0, s66, 0xe000
	s_nop 0
	global_load_lds_dwordx4 v160, s[58:59]
	s_waitcnt lgkmcnt(8)
	s_barrier
	s_waitcnt lgkmcnt(7)
	v_mfma_f32_16x16x32_bf16 v[124:127], v[128:131], v[144:147], v[124:127]
	v_mfma_f32_16x16x32_bf16 v[120:123], v[136:139], v[144:147], v[120:123]
	s_waitcnt lgkmcnt(6)
	v_mfma_f32_16x16x32_bf16 v[108:111], v[128:131], v[162:165], v[108:111]
	v_mfma_f32_16x16x32_bf16 v[104:107], v[136:139], v[162:165], v[104:107]
	s_waitcnt lgkmcnt(5)
	v_mfma_f32_16x16x32_bf16 v[92:95], v[128:131], v[170:173], v[92:95]
	v_mfma_f32_16x16x32_bf16 v[88:91], v[136:139], v[170:173], v[88:91]
	s_waitcnt lgkmcnt(4)
	v_mfma_f32_16x16x32_bf16 v[76:79], v[128:131], v[198:201], v[76:79]
	v_mfma_f32_16x16x32_bf16 v[72:75], v[136:139], v[198:201], v[72:75]
	s_waitcnt lgkmcnt(3)
	v_mfma_f32_16x16x32_bf16 v[124:127], v[132:135], v[148:151], v[124:127]
	v_mfma_f32_16x16x32_bf16 v[120:123], v[140:143], v[148:151], v[120:123]
	s_waitcnt lgkmcnt(2)
	v_mfma_f32_16x16x32_bf16 v[108:111], v[132:135], v[166:169], v[108:111]
	v_mfma_f32_16x16x32_bf16 v[104:107], v[140:143], v[166:169], v[104:107]
	s_waitcnt lgkmcnt(1)
	v_mfma_f32_16x16x32_bf16 v[92:95], v[132:135], v[188:191], v[92:95]
	v_mfma_f32_16x16x32_bf16 v[88:91], v[140:143], v[188:191], v[88:91]
	s_waitcnt lgkmcnt(0)
	v_mfma_f32_16x16x32_bf16 v[76:79], v[132:135], v[202:205], v[76:79]
	v_mfma_f32_16x16x32_bf16 v[72:75], v[140:143], v[202:205], v[72:75]
	s_barrier
	s_add_i32 s28, 0, 0x14000
	v_add_u32_e32 v174, s28, v195
	s_add_i32 s29, s82, s65
	ds_read_b128 v[206:209], v174
	ds_read_b128 v[210:213], v174 offset:1024
	ds_read_b128 v[214:217], v174 offset:2048
	ds_read_b128 v[232:235], v174 offset:3072
	s_mov_b32 m0, s29
	s_nop 0
	global_load_lds_dwordx4 v176, s[62:63]
	s_add_i32 m0, s29, 0x2000
	s_nop 0
	global_load_lds_dwordx4 v156, s[62:63]
	s_barrier
	s_waitcnt lgkmcnt(3)
	v_mfma_f32_16x16x32_bf16 v[116:119], v[206:209], v[144:147], v[116:119]
	s_waitcnt lgkmcnt(1)
	v_mfma_f32_16x16x32_bf16 v[112:115], v[214:217], v[144:147], v[112:115]
	v_mfma_f32_16x16x32_bf16 v[100:103], v[206:209], v[162:165], v[100:103]
	v_mfma_f32_16x16x32_bf16 v[96:99], v[214:217], v[162:165], v[96:99]
	v_mfma_f32_16x16x32_bf16 v[84:87], v[206:209], v[170:173], v[84:87]
	v_mfma_f32_16x16x32_bf16 v[80:83], v[214:217], v[170:173], v[80:83]
	v_mfma_f32_16x16x32_bf16 v[68:71], v[206:209], v[198:201], v[68:71]
	v_mfma_f32_16x16x32_bf16 v[64:67], v[214:217], v[198:201], v[64:67]
	v_mfma_f32_16x16x32_bf16 v[116:119], v[210:213], v[148:151], v[116:119]
	s_waitcnt lgkmcnt(0)
	v_mfma_f32_16x16x32_bf16 v[112:115], v[232:235], v[148:151], v[112:115]
	v_mfma_f32_16x16x32_bf16 v[100:103], v[210:213], v[166:169], v[100:103]
	v_mfma_f32_16x16x32_bf16 v[96:99], v[232:235], v[166:169], v[96:99]
	v_mfma_f32_16x16x32_bf16 v[84:87], v[210:213], v[188:191], v[84:87]
	v_mfma_f32_16x16x32_bf16 v[80:83], v[232:235], v[188:191], v[80:83]
	v_mfma_f32_16x16x32_bf16 v[68:71], v[210:213], v[202:205], v[68:71]
	v_mfma_f32_16x16x32_bf16 v[64:67], v[232:235], v[202:205], v[64:67]
	s_mov_b32 m0, s66
	s_barrier
	ds_read_b128 v[144:147], v196 offset:16384
	ds_read_b128 v[162:165], v196 offset:18432
	ds_read_b128 v[170:173], v196 offset:20480
	ds_read_b128 v[198:201], v196 offset:22528
	ds_read_b128 v[148:151], v196 offset:17408
	ds_read_b128 v[166:169], v196 offset:19456
	ds_read_b128 v[188:191], v196 offset:21504
	ds_read_b128 v[202:205], v196 offset:23552
	global_load_lds_dwordx4 v152, s[60:61]
	s_mov_b32 m0, s67
	s_nop 0
	global_load_lds_dwordx4 v154, s[60:61]
	s_barrier
	s_waitcnt lgkmcnt(7)
	v_mfma_f32_16x16x32_bf16 v[60:63], v[128:131], v[144:147], v[60:63]
	v_mfma_f32_16x16x32_bf16 v[56:59], v[136:139], v[144:147], v[56:59]
	s_waitcnt lgkmcnt(6)
	v_mfma_f32_16x16x32_bf16 v[44:47], v[128:131], v[162:165], v[44:47]
	v_mfma_f32_16x16x32_bf16 v[40:43], v[136:139], v[162:165], v[40:43]
	s_waitcnt lgkmcnt(5)
	v_mfma_f32_16x16x32_bf16 v[28:31], v[128:131], v[170:173], v[28:31]
	v_mfma_f32_16x16x32_bf16 v[24:27], v[136:139], v[170:173], v[24:27]
	s_waitcnt lgkmcnt(4)
	v_mfma_f32_16x16x32_bf16 v[12:15], v[128:131], v[198:201], v[12:15]
	v_mfma_f32_16x16x32_bf16 v[8:11], v[136:139], v[198:201], v[8:11]
	s_waitcnt lgkmcnt(3)
	v_mfma_f32_16x16x32_bf16 v[60:63], v[132:135], v[148:151], v[60:63]
	v_mfma_f32_16x16x32_bf16 v[56:59], v[140:143], v[148:151], v[56:59]
	s_waitcnt lgkmcnt(2)
	v_mfma_f32_16x16x32_bf16 v[44:47], v[132:135], v[166:169], v[44:47]
	v_mfma_f32_16x16x32_bf16 v[40:43], v[140:143], v[166:169], v[40:43]
	s_waitcnt lgkmcnt(1)
	v_mfma_f32_16x16x32_bf16 v[28:31], v[132:135], v[188:191], v[28:31]
	v_mfma_f32_16x16x32_bf16 v[24:27], v[140:143], v[188:191], v[24:27]
	s_waitcnt lgkmcnt(0)
	v_mfma_f32_16x16x32_bf16 v[12:15], v[132:135], v[202:205], v[12:15]
	v_mfma_f32_16x16x32_bf16 v[8:11], v[140:143], v[202:205], v[8:11]
	s_barrier
	s_add_u32 s98, s62, s4
	s_addc_u32 s99, s63, 0
	s_add_i32 s28, s28, s65
	s_mov_b32 m0, s28
	s_nop 0
	global_load_lds_dwordx4 v176, s[98:99]
	s_add_i32 m0, s28, 0x2000
	s_nop 0
	global_load_lds_dwordx4 v156, s[98:99]
	s_waitcnt vmcnt(6)
	s_barrier
	v_mfma_f32_16x16x32_bf16 v[52:55], v[206:209], v[144:147], v[52:55]
	v_mfma_f32_16x16x32_bf16 v[48:51], v[214:217], v[144:147], v[48:51]
	v_mfma_f32_16x16x32_bf16 v[36:39], v[206:209], v[162:165], v[36:39]
	v_mfma_f32_16x16x32_bf16 v[32:35], v[214:217], v[162:165], v[32:35]
	v_mfma_f32_16x16x32_bf16 v[20:23], v[206:209], v[170:173], v[20:23]
	v_mfma_f32_16x16x32_bf16 v[16:19], v[214:217], v[170:173], v[16:19]
	v_mfma_f32_16x16x32_bf16 v[4:7], v[206:209], v[198:201], v[4:7]
	v_mfma_f32_16x16x32_bf16 v[0:3], v[214:217], v[198:201], v[0:3]
	v_mfma_f32_16x16x32_bf16 v[52:55], v[210:213], v[148:151], v[52:55]
	v_mfma_f32_16x16x32_bf16 v[48:51], v[232:235], v[148:151], v[48:51]
	v_mfma_f32_16x16x32_bf16 v[36:39], v[210:213], v[166:169], v[36:39]
	v_mfma_f32_16x16x32_bf16 v[32:35], v[232:235], v[166:169], v[32:35]
	v_mfma_f32_16x16x32_bf16 v[20:23], v[210:213], v[188:191], v[20:23]
	v_mfma_f32_16x16x32_bf16 v[16:19], v[232:235], v[188:191], v[16:19]
	v_mfma_f32_16x16x32_bf16 v[4:7], v[210:213], v[202:205], v[4:7]
	v_mfma_f32_16x16x32_bf16 v[0:3], v[232:235], v[202:205], v[0:3]
	s_add_i32 s28, 0, 0x18000
	v_add_u32_e32 v140, s28, v195
	s_barrier
	ds_read_b128 v[128:131], v140
	ds_read_b128 v[132:135], v140 offset:1024
	ds_read_b128 v[136:139], v140 offset:2048
	ds_read_b128 v[140:143], v140 offset:3072
	s_add_u32 s100, s60, s4
	s_addc_u32 s101, s61, 0
	s_mov_b32 m0, s68
	ds_read_b128 v[144:147], v196 offset:32768
	ds_read_b128 v[162:165], v196 offset:34816
	ds_read_b128 v[170:173], v196 offset:36864
	ds_read_b128 v[198:201], v196 offset:38912
	ds_read_b128 v[148:151], v196 offset:33792
	ds_read_b128 v[166:169], v196 offset:35840
	ds_read_b128 v[188:191], v196 offset:37888
	ds_read_b128 v[202:205], v196 offset:39936
	global_load_lds_dwordx4 v152, s[100:101]
	s_mov_b32 m0, s69
	s_nop 0
	global_load_lds_dwordx4 v154, s[100:101]
	s_waitcnt lgkmcnt(8)
	s_barrier
	s_waitcnt lgkmcnt(7)
	v_mfma_f32_16x16x32_bf16 v[124:127], v[128:131], v[144:147], v[124:127]
	v_mfma_f32_16x16x32_bf16 v[120:123], v[136:139], v[144:147], v[120:123]
	s_waitcnt lgkmcnt(6)
	v_mfma_f32_16x16x32_bf16 v[108:111], v[128:131], v[162:165], v[108:111]
	v_mfma_f32_16x16x32_bf16 v[104:107], v[136:139], v[162:165], v[104:107]
	s_waitcnt lgkmcnt(5)
	v_mfma_f32_16x16x32_bf16 v[92:95], v[128:131], v[170:173], v[92:95]
	v_mfma_f32_16x16x32_bf16 v[88:91], v[136:139], v[170:173], v[88:91]
	s_waitcnt lgkmcnt(4)
	v_mfma_f32_16x16x32_bf16 v[76:79], v[128:131], v[198:201], v[76:79]
	v_mfma_f32_16x16x32_bf16 v[72:75], v[136:139], v[198:201], v[72:75]
	s_waitcnt lgkmcnt(3)
	v_mfma_f32_16x16x32_bf16 v[124:127], v[132:135], v[148:151], v[124:127]
	v_mfma_f32_16x16x32_bf16 v[120:123], v[140:143], v[148:151], v[120:123]
	s_waitcnt lgkmcnt(2)
	v_mfma_f32_16x16x32_bf16 v[108:111], v[132:135], v[166:169], v[108:111]
	v_mfma_f32_16x16x32_bf16 v[104:107], v[140:143], v[166:169], v[104:107]
	s_waitcnt lgkmcnt(1)
	v_mfma_f32_16x16x32_bf16 v[92:95], v[132:135], v[188:191], v[92:95]
	v_mfma_f32_16x16x32_bf16 v[88:91], v[140:143], v[188:191], v[88:91]
	s_waitcnt lgkmcnt(0)
	v_mfma_f32_16x16x32_bf16 v[76:79], v[132:135], v[202:205], v[76:79]
	v_mfma_f32_16x16x32_bf16 v[72:75], v[140:143], v[202:205], v[72:75]
	s_barrier
	s_add_i32 s29, 0, 0x1c000
	s_add_i32 s28, s28, s65
	v_add_u32_e32 v197, s29, v195
	s_add_i32 m0, s28, 0xffffff80
	ds_read_b128 v[206:209], v197
	ds_read_b128 v[210:213], v197 offset:1024
	ds_read_b128 v[214:217], v197 offset:2048
	ds_read_b128 v[232:235], v197 offset:3072
	global_load_lds_dwordx4 v176, s[62:63] offset:128
	s_add_i32 m0, s28, 0x1f80
	s_nop 0
	global_load_lds_dwordx4 v156, s[62:63] offset:128
	s_barrier
	s_waitcnt lgkmcnt(3)
	v_mfma_f32_16x16x32_bf16 v[116:119], v[206:209], v[144:147], v[116:119]
	s_waitcnt lgkmcnt(1)
	v_mfma_f32_16x16x32_bf16 v[112:115], v[214:217], v[144:147], v[112:115]
	v_mfma_f32_16x16x32_bf16 v[100:103], v[206:209], v[162:165], v[100:103]
	v_mfma_f32_16x16x32_bf16 v[96:99], v[214:217], v[162:165], v[96:99]
	v_mfma_f32_16x16x32_bf16 v[84:87], v[206:209], v[170:173], v[84:87]
	v_mfma_f32_16x16x32_bf16 v[80:83], v[214:217], v[170:173], v[80:83]
	v_mfma_f32_16x16x32_bf16 v[68:71], v[206:209], v[198:201], v[68:71]
	v_mfma_f32_16x16x32_bf16 v[64:67], v[214:217], v[198:201], v[64:67]
	v_mfma_f32_16x16x32_bf16 v[116:119], v[210:213], v[148:151], v[116:119]
	s_waitcnt lgkmcnt(0)
	v_mfma_f32_16x16x32_bf16 v[112:115], v[232:235], v[148:151], v[112:115]
	v_mfma_f32_16x16x32_bf16 v[100:103], v[210:213], v[166:169], v[100:103]
	v_mfma_f32_16x16x32_bf16 v[96:99], v[232:235], v[166:169], v[96:99]
	v_mfma_f32_16x16x32_bf16 v[84:87], v[210:213], v[188:191], v[84:87]
	v_mfma_f32_16x16x32_bf16 v[80:83], v[232:235], v[188:191], v[80:83]
	v_mfma_f32_16x16x32_bf16 v[68:71], v[210:213], v[202:205], v[68:71]
	v_mfma_f32_16x16x32_bf16 v[64:67], v[232:235], v[202:205], v[64:67]
	s_add_i32 m0, s71, 0xffffff80
	s_barrier
	ds_read_b128 v[144:147], v196 offset:49152
	ds_read_b128 v[162:165], v196 offset:51200
	ds_read_b128 v[170:173], v196 offset:53248
	ds_read_b128 v[198:201], v196 offset:55296
	ds_read_b128 v[148:151], v196 offset:50176
	ds_read_b128 v[166:169], v196 offset:52224
	ds_read_b128 v[188:191], v196 offset:54272
	ds_read_b128 v[202:205], v196 offset:56320
	global_load_lds_dwordx4 v152, s[60:61] offset:128
	s_add_i32 m0, s72, 0xffffff80
	s_nop 0
	global_load_lds_dwordx4 v154, s[60:61] offset:128
	s_barrier
	s_waitcnt lgkmcnt(7)
	v_mfma_f32_16x16x32_bf16 v[60:63], v[128:131], v[144:147], v[60:63]
	v_mfma_f32_16x16x32_bf16 v[56:59], v[136:139], v[144:147], v[56:59]
	s_waitcnt lgkmcnt(6)
	v_mfma_f32_16x16x32_bf16 v[44:47], v[128:131], v[162:165], v[44:47]
	v_mfma_f32_16x16x32_bf16 v[40:43], v[136:139], v[162:165], v[40:43]
	s_waitcnt lgkmcnt(5)
	v_mfma_f32_16x16x32_bf16 v[28:31], v[128:131], v[170:173], v[28:31]
	v_mfma_f32_16x16x32_bf16 v[24:27], v[136:139], v[170:173], v[24:27]
	s_waitcnt lgkmcnt(4)
	v_mfma_f32_16x16x32_bf16 v[12:15], v[128:131], v[198:201], v[12:15]
	v_mfma_f32_16x16x32_bf16 v[8:11], v[136:139], v[198:201], v[8:11]
	s_waitcnt lgkmcnt(3)
	v_mfma_f32_16x16x32_bf16 v[60:63], v[132:135], v[148:151], v[60:63]
	v_mfma_f32_16x16x32_bf16 v[56:59], v[140:143], v[148:151], v[56:59]
	s_waitcnt lgkmcnt(2)
	v_mfma_f32_16x16x32_bf16 v[44:47], v[132:135], v[166:169], v[44:47]
	v_mfma_f32_16x16x32_bf16 v[40:43], v[140:143], v[166:169], v[40:43]
	s_waitcnt lgkmcnt(1)
	v_mfma_f32_16x16x32_bf16 v[28:31], v[132:135], v[188:191], v[28:31]
	v_mfma_f32_16x16x32_bf16 v[24:27], v[140:143], v[188:191], v[24:27]
	s_waitcnt lgkmcnt(0)
	v_mfma_f32_16x16x32_bf16 v[12:15], v[132:135], v[202:205], v[12:15]
	v_mfma_f32_16x16x32_bf16 v[8:11], v[140:143], v[202:205], v[8:11]
	s_barrier
	s_add_i32 s28, s29, s65
	s_add_i32 m0, s28, 0xffffff80
	s_nop 0
	global_load_lds_dwordx4 v176, s[98:99] offset:128
	s_add_i32 m0, s28, 0x1f80
	s_nop 0
	global_load_lds_dwordx4 v156, s[98:99] offset:128
	s_waitcnt vmcnt(6)
	s_barrier
	v_mfma_f32_16x16x32_bf16 v[52:55], v[206:209], v[144:147], v[52:55]
	v_mfma_f32_16x16x32_bf16 v[48:51], v[214:217], v[144:147], v[48:51]
	v_mfma_f32_16x16x32_bf16 v[36:39], v[206:209], v[162:165], v[36:39]
	v_mfma_f32_16x16x32_bf16 v[32:35], v[214:217], v[162:165], v[32:35]
	v_mfma_f32_16x16x32_bf16 v[20:23], v[206:209], v[170:173], v[20:23]
	v_mfma_f32_16x16x32_bf16 v[16:19], v[214:217], v[170:173], v[16:19]
	v_mfma_f32_16x16x32_bf16 v[4:7], v[206:209], v[198:201], v[4:7]
	v_mfma_f32_16x16x32_bf16 v[0:3], v[214:217], v[198:201], v[0:3]
	v_mfma_f32_16x16x32_bf16 v[52:55], v[210:213], v[148:151], v[52:55]
	v_mfma_f32_16x16x32_bf16 v[48:51], v[232:235], v[148:151], v[48:51]
	v_mfma_f32_16x16x32_bf16 v[36:39], v[210:213], v[166:169], v[36:39]
	v_mfma_f32_16x16x32_bf16 v[32:35], v[232:235], v[166:169], v[32:35]
	v_mfma_f32_16x16x32_bf16 v[20:23], v[210:213], v[188:191], v[20:23]
	v_mfma_f32_16x16x32_bf16 v[16:19], v[232:235], v[188:191], v[16:19]
	v_mfma_f32_16x16x32_bf16 v[4:7], v[210:213], v[202:205], v[4:7]
	v_mfma_f32_16x16x32_bf16 v[0:3], v[232:235], v[202:205], v[0:3]
	s_add_u32 s58, s58, 0x100
	s_addc_u32 s59, s59, 0
	s_add_u32 s21, s21, 0x100
	s_addc_u32 s80, s80, 0
	s_cmp_ge_i32 s81, s79
	s_mov_b32 s60, s81
	s_barrier
	s_cbranch_scc0 .LBB0_1282
	s_cmp_gt_i32 s24, -1
	s_mov_b64 s[58:59], -1
	s_cbranch_scc0 .LBB0_1285
	s_lshl_b64 s[58:59], s[24:25], 17
	v_mov_b32_e32 v128, v231
	s_add_u32 s58, s37, s58
	s_addc_u32 s59, s46, s59
	v_ashrrev_i32_e32 v129, 31, v128
	v_lshl_add_u64 v[128:129], v[128:129], 4, s[58:59]
	v_add_co_u32_e32 v134, vcc, s36, v128
	v_cvt_pk_bf16_f32 v130, v124, v125
	v_cvt_pk_bf16_f32 v131, v126, v127
	v_cvt_pk_bf16_f32 v132, v120, v121
	v_cvt_pk_bf16_f32 v133, v122, v123
	s_nop 1
	v_addc_co_u32_e32 v135, vcc, 0, v129, vcc
	s_movk_i32 s5, 0x4000
	global_store_dwordx4 v[128:129], v[130:133], off
	s_mov_b64 s[58:59], 0
	s_nop 0
	v_cvt_pk_bf16_f32 v130, v108, v109
	v_cvt_pk_bf16_f32 v131, v110, v111
	v_cvt_pk_bf16_f32 v132, v104, v105
	v_cvt_pk_bf16_f32 v133, v106, v107
	global_store_dwordx4 v[134:135], v[130:133], off
	v_add_co_u32_e32 v134, vcc, s5, v128
	s_movk_i32 s5, 0x6000
	s_nop 0
	v_addc_co_u32_e32 v135, vcc, 0, v129, vcc
	v_cvt_pk_bf16_f32 v130, v92, v93
	v_cvt_pk_bf16_f32 v131, v94, v95
	v_cvt_pk_bf16_f32 v132, v88, v89
	v_cvt_pk_bf16_f32 v133, v90, v91
	global_store_dwordx4 v[134:135], v[130:133], off
	v_add_co_u32_e32 v134, vcc, s5, v128
	s_nop 0
	v_cvt_pk_bf16_f32 v130, v76, v77
	v_cvt_pk_bf16_f32 v131, v78, v79
	v_cvt_pk_bf16_f32 v132, v72, v73
	v_cvt_pk_bf16_f32 v133, v74, v75
	s_nop 0
	v_addc_co_u32_e32 v135, vcc, 0, v129, vcc
	global_store_dwordx4 v[134:135], v[130:133], off
	v_add_co_u32_e32 v134, vcc, s92, v128
	s_mov_b32 s5, 0xa000
	s_nop 0
	v_addc_co_u32_e32 v135, vcc, 0, v129, vcc
	v_cvt_pk_bf16_f32 v130, v116, v117
	v_cvt_pk_bf16_f32 v131, v118, v119
	v_cvt_pk_bf16_f32 v132, v112, v113
	v_cvt_pk_bf16_f32 v133, v114, v115
	global_store_dwordx4 v[134:135], v[130:133], off
	v_add_co_u32_e32 v134, vcc, s5, v128
	s_mov_b32 s5, 0xc000
	s_nop 0
	v_addc_co_u32_e32 v135, vcc, 0, v129, vcc
	v_cvt_pk_bf16_f32 v130, v100, v101
	v_cvt_pk_bf16_f32 v131, v102, v103
	v_cvt_pk_bf16_f32 v132, v96, v97
	v_cvt_pk_bf16_f32 v133, v98, v99
	global_store_dwordx4 v[134:135], v[130:133], off
	v_add_co_u32_e32 v134, vcc, s5, v128
	s_mov_b32 s5, 0xe000
	s_nop 0
	v_addc_co_u32_e32 v135, vcc, 0, v129, vcc
	v_cvt_pk_bf16_f32 v130, v84, v85
	v_cvt_pk_bf16_f32 v131, v86, v87
	v_cvt_pk_bf16_f32 v132, v80, v81
	v_cvt_pk_bf16_f32 v133, v82, v83
	global_store_dwordx4 v[134:135], v[130:133], off
	v_add_co_u32_e32 v134, vcc, s5, v128
	s_mov_b32 s5, 0x10000
	s_nop 0
	v_addc_co_u32_e32 v135, vcc, 0, v129, vcc
	v_cvt_pk_bf16_f32 v130, v68, v69
	v_cvt_pk_bf16_f32 v131, v70, v71
	v_cvt_pk_bf16_f32 v132, v64, v65
	v_cvt_pk_bf16_f32 v133, v66, v67
	global_store_dwordx4 v[134:135], v[130:133], off
	v_add_co_u32_e32 v134, vcc, s5, v128
	s_mov_b32 s5, 0x12000
	s_nop 0
	v_addc_co_u32_e32 v135, vcc, 0, v129, vcc
	v_cvt_pk_bf16_f32 v130, v60, v61
	v_cvt_pk_bf16_f32 v131, v62, v63
	v_cvt_pk_bf16_f32 v132, v56, v57
	v_cvt_pk_bf16_f32 v133, v58, v59
	global_store_dwordx4 v[134:135], v[130:133], off
	v_add_co_u32_e32 v134, vcc, s5, v128
	s_mov_b32 s5, 0x14000
	s_nop 0
	v_addc_co_u32_e32 v135, vcc, 0, v129, vcc
	v_cvt_pk_bf16_f32 v130, v44, v45
	v_cvt_pk_bf16_f32 v131, v46, v47
	v_cvt_pk_bf16_f32 v132, v40, v41
	v_cvt_pk_bf16_f32 v133, v42, v43
	global_store_dwordx4 v[134:135], v[130:133], off
	v_add_co_u32_e32 v134, vcc, s5, v128
	s_mov_b32 s5, 0x16000
	s_nop 0
	v_addc_co_u32_e32 v135, vcc, 0, v129, vcc
	v_cvt_pk_bf16_f32 v130, v28, v29
	v_cvt_pk_bf16_f32 v131, v30, v31
	v_cvt_pk_bf16_f32 v132, v24, v25
	v_cvt_pk_bf16_f32 v133, v26, v27
	global_store_dwordx4 v[134:135], v[130:133], off
	v_add_co_u32_e32 v134, vcc, s5, v128
	s_mov_b32 s5, 0x18000
	s_nop 0
	v_addc_co_u32_e32 v135, vcc, 0, v129, vcc
	v_cvt_pk_bf16_f32 v130, v12, v13
	v_cvt_pk_bf16_f32 v131, v14, v15
	v_cvt_pk_bf16_f32 v132, v8, v9
	v_cvt_pk_bf16_f32 v133, v10, v11
	global_store_dwordx4 v[134:135], v[130:133], off
	v_add_co_u32_e32 v134, vcc, s5, v128
	s_mov_b32 s5, 0x1a000
	s_nop 0
	v_addc_co_u32_e32 v135, vcc, 0, v129, vcc
	v_cvt_pk_bf16_f32 v130, v52, v53
	v_cvt_pk_bf16_f32 v131, v54, v55
	v_cvt_pk_bf16_f32 v132, v48, v49
	v_cvt_pk_bf16_f32 v133, v50, v51
	global_store_dwordx4 v[134:135], v[130:133], off
	v_add_co_u32_e32 v134, vcc, s5, v128
	s_mov_b32 s5, 0x1c000
	s_nop 0
	v_addc_co_u32_e32 v135, vcc, 0, v129, vcc
	v_cvt_pk_bf16_f32 v130, v36, v37
	v_cvt_pk_bf16_f32 v131, v38, v39
	v_cvt_pk_bf16_f32 v132, v32, v33
	v_cvt_pk_bf16_f32 v133, v34, v35
	global_store_dwordx4 v[134:135], v[130:133], off
	v_add_co_u32_e32 v134, vcc, s5, v128
	s_nop 0
	v_cvt_pk_bf16_f32 v130, v20, v21
	v_cvt_pk_bf16_f32 v131, v22, v23
	v_cvt_pk_bf16_f32 v132, v16, v17
	v_cvt_pk_bf16_f32 v133, v18, v19
	s_nop 0
	v_addc_co_u32_e32 v135, vcc, 0, v129, vcc
	v_add_co_u32_e32 v128, vcc, 0x1e000, v128
	global_store_dwordx4 v[134:135], v[130:133], off
	s_nop 0
	v_addc_co_u32_e32 v129, vcc, 0, v129, vcc
	v_cvt_pk_bf16_f32 v130, v4, v5
	v_cvt_pk_bf16_f32 v131, v6, v7
	v_cvt_pk_bf16_f32 v132, v0, v1
	v_cvt_pk_bf16_f32 v133, v2, v3
	global_store_dwordx4 v[128:129], v[130:133], off

.LBB0_1436:
	s_add_u32 s28, s6, 0xfffc0080
	s_addc_u32 s29, s7, -1
	s_add_i32 s71, 0, 0x10000
	v_add_u32_e32 v140, s71, v200
	ds_read_b128 v[128:131], v140
	ds_read_b128 v[132:135], v140 offset:1024
	ds_read_b128 v[136:139], v140 offset:2048
	ds_read_b128 v[140:143], v140 offset:3072
	s_cmp_eq_u32 s70, 12
	s_cselect_b32 s53, s17, s29
	s_cselect_b32 s52, s66, s28
	s_cselect_b32 s51, s13, s69
	s_cselect_b32 s50, s67, s68
	s_add_i32 m0, s56, 0xc000
	ds_read_b128 v[144:147], v201
	ds_read_b128 v[152:155], v201 offset:2048
	ds_read_b128 v[170:173], v201 offset:4096
	ds_read_b128 v[192:195], v201 offset:6144
	ds_read_b128 v[148:151], v201 offset:1024
	ds_read_b128 v[166:169], v201 offset:3072
	ds_read_b128 v[188:191], v201 offset:5120
	ds_read_b128 v[202:205], v201 offset:7168
	global_load_lds_dwordx4 v162, s[6:7]
	s_add_i32 m0, s56, 0xe000
	s_nop 0
	global_load_lds_dwordx4 v164, s[6:7]
	s_waitcnt lgkmcnt(8)
	s_barrier
	s_waitcnt lgkmcnt(7)
	v_mfma_f32_16x16x32_bf16 v[124:127], v[128:131], v[144:147], v[124:127]
	v_mfma_f32_16x16x32_bf16 v[116:119], v[136:139], v[144:147], v[116:119]
	s_waitcnt lgkmcnt(6)
	v_mfma_f32_16x16x32_bf16 v[108:111], v[128:131], v[152:155], v[108:111]
	v_mfma_f32_16x16x32_bf16 v[100:103], v[136:139], v[152:155], v[100:103]
	s_waitcnt lgkmcnt(5)
	v_mfma_f32_16x16x32_bf16 v[92:95], v[128:131], v[170:173], v[92:95]
	v_mfma_f32_16x16x32_bf16 v[84:87], v[136:139], v[170:173], v[84:87]
	s_waitcnt lgkmcnt(4)
	v_mfma_f32_16x16x32_bf16 v[76:79], v[128:131], v[192:195], v[76:79]
	v_mfma_f32_16x16x32_bf16 v[68:71], v[136:139], v[192:195], v[68:71]
	s_waitcnt lgkmcnt(3)
	v_mfma_f32_16x16x32_bf16 v[124:127], v[132:135], v[148:151], v[124:127]
	v_mfma_f32_16x16x32_bf16 v[116:119], v[140:143], v[148:151], v[116:119]
	s_waitcnt lgkmcnt(2)
	v_mfma_f32_16x16x32_bf16 v[108:111], v[132:135], v[166:169], v[108:111]
	v_mfma_f32_16x16x32_bf16 v[100:103], v[140:143], v[166:169], v[100:103]
	s_waitcnt lgkmcnt(1)
	v_mfma_f32_16x16x32_bf16 v[92:95], v[132:135], v[188:191], v[92:95]
	v_mfma_f32_16x16x32_bf16 v[84:87], v[140:143], v[188:191], v[84:87]
	s_waitcnt lgkmcnt(0)
	v_mfma_f32_16x16x32_bf16 v[76:79], v[132:135], v[202:205], v[76:79]
	v_mfma_f32_16x16x32_bf16 v[68:71], v[140:143], v[202:205], v[68:71]
	s_barrier
	s_add_i32 s28, 0, 0x14000
	v_add_u32_e32 v174, s28, v200
	s_add_i32 s29, s71, s55
	ds_read_b128 v[206:209], v174
	ds_read_b128 v[210:213], v174 offset:1024
	ds_read_b128 v[214:217], v174 offset:2048
	ds_read_b128 v[232:235], v174 offset:3072
	s_mov_b32 m0, s29
	s_nop 0
	global_load_lds_dwordx4 v176, s[50:51]
	s_add_i32 m0, s29, 0x2000
	s_nop 0
	global_load_lds_dwordx4 v160, s[50:51]
	s_barrier
	s_waitcnt lgkmcnt(3)
	v_mfma_f32_16x16x32_bf16 v[120:123], v[206:209], v[144:147], v[120:123]
	s_waitcnt lgkmcnt(1)
	v_mfma_f32_16x16x32_bf16 v[112:115], v[214:217], v[144:147], v[112:115]
	v_mfma_f32_16x16x32_bf16 v[104:107], v[206:209], v[152:155], v[104:107]
	v_mfma_f32_16x16x32_bf16 v[96:99], v[214:217], v[152:155], v[96:99]
	v_mfma_f32_16x16x32_bf16 v[88:91], v[206:209], v[170:173], v[88:91]
	v_mfma_f32_16x16x32_bf16 v[80:83], v[214:217], v[170:173], v[80:83]
	v_mfma_f32_16x16x32_bf16 v[72:75], v[206:209], v[192:195], v[72:75]
	v_mfma_f32_16x16x32_bf16 v[64:67], v[214:217], v[192:195], v[64:67]
	v_mfma_f32_16x16x32_bf16 v[120:123], v[210:213], v[148:151], v[120:123]
	s_waitcnt lgkmcnt(0)
	v_mfma_f32_16x16x32_bf16 v[112:115], v[232:235], v[148:151], v[112:115]
	v_mfma_f32_16x16x32_bf16 v[104:107], v[210:213], v[166:169], v[104:107]
	v_mfma_f32_16x16x32_bf16 v[96:99], v[232:235], v[166:169], v[96:99]
	v_mfma_f32_16x16x32_bf16 v[88:91], v[210:213], v[188:191], v[88:91]
	v_mfma_f32_16x16x32_bf16 v[80:83], v[232:235], v[188:191], v[80:83]
	v_mfma_f32_16x16x32_bf16 v[72:75], v[210:213], v[202:205], v[72:75]
	v_mfma_f32_16x16x32_bf16 v[64:67], v[232:235], v[202:205], v[64:67]
	s_mov_b32 m0, s56
	s_barrier
	ds_read_b128 v[144:147], v201 offset:16384
	ds_read_b128 v[152:155], v201 offset:18432
	ds_read_b128 v[170:173], v201 offset:20480
	ds_read_b128 v[192:195], v201 offset:22528
	ds_read_b128 v[148:151], v201 offset:17408
	ds_read_b128 v[166:169], v201 offset:19456
	ds_read_b128 v[188:191], v201 offset:21504
	ds_read_b128 v[202:205], v201 offset:23552
	global_load_lds_dwordx4 v156, s[52:53]
	s_mov_b32 m0, s57
	s_nop 0
	global_load_lds_dwordx4 v158, s[52:53]
	s_barrier
	s_waitcnt lgkmcnt(7)
	v_mfma_f32_16x16x32_bf16 v[60:63], v[128:131], v[144:147], v[60:63]
	v_mfma_f32_16x16x32_bf16 v[52:55], v[136:139], v[144:147], v[52:55]
	s_waitcnt lgkmcnt(6)
	v_mfma_f32_16x16x32_bf16 v[44:47], v[128:131], v[152:155], v[44:47]
	v_mfma_f32_16x16x32_bf16 v[36:39], v[136:139], v[152:155], v[36:39]
	s_waitcnt lgkmcnt(5)
	v_mfma_f32_16x16x32_bf16 v[28:31], v[128:131], v[170:173], v[28:31]
	v_mfma_f32_16x16x32_bf16 v[20:23], v[136:139], v[170:173], v[20:23]
	s_waitcnt lgkmcnt(4)
	v_mfma_f32_16x16x32_bf16 v[12:15], v[128:131], v[192:195], v[12:15]
	v_mfma_f32_16x16x32_bf16 v[4:7], v[136:139], v[192:195], v[4:7]
	s_waitcnt lgkmcnt(3)
	v_mfma_f32_16x16x32_bf16 v[60:63], v[132:135], v[148:151], v[60:63]
	v_mfma_f32_16x16x32_bf16 v[52:55], v[140:143], v[148:151], v[52:55]
	s_waitcnt lgkmcnt(2)
	v_mfma_f32_16x16x32_bf16 v[44:47], v[132:135], v[166:169], v[44:47]
	v_mfma_f32_16x16x32_bf16 v[36:39], v[140:143], v[166:169], v[36:39]
	s_waitcnt lgkmcnt(1)
	v_mfma_f32_16x16x32_bf16 v[28:31], v[132:135], v[188:191], v[28:31]
	v_mfma_f32_16x16x32_bf16 v[20:23], v[140:143], v[188:191], v[20:23]
	s_waitcnt lgkmcnt(0)
	v_mfma_f32_16x16x32_bf16 v[12:15], v[132:135], v[202:205], v[12:15]
	v_mfma_f32_16x16x32_bf16 v[4:7], v[140:143], v[202:205], v[4:7]
	s_barrier
	s_add_u32 s72, s50, 0x40000
	s_addc_u32 s73, s51, 0
	s_add_i32 s28, s28, s55
	s_mov_b32 m0, s28
	s_nop 0
	global_load_lds_dwordx4 v176, s[72:73]
	s_add_i32 m0, s28, 0x2000
	s_nop 0
	global_load_lds_dwordx4 v160, s[72:73]
	s_waitcnt vmcnt(6)
	s_barrier
	v_mfma_f32_16x16x32_bf16 v[56:59], v[206:209], v[144:147], v[56:59]
	v_mfma_f32_16x16x32_bf16 v[48:51], v[214:217], v[144:147], v[48:51]
	v_mfma_f32_16x16x32_bf16 v[40:43], v[206:209], v[152:155], v[40:43]
	v_mfma_f32_16x16x32_bf16 v[32:35], v[214:217], v[152:155], v[32:35]
	v_mfma_f32_16x16x32_bf16 v[24:27], v[206:209], v[170:173], v[24:27]
	v_mfma_f32_16x16x32_bf16 v[16:19], v[214:217], v[170:173], v[16:19]
	v_mfma_f32_16x16x32_bf16 v[8:11], v[206:209], v[192:195], v[8:11]
	v_mfma_f32_16x16x32_bf16 v[0:3], v[214:217], v[192:195], v[0:3]
	v_mfma_f32_16x16x32_bf16 v[56:59], v[210:213], v[148:151], v[56:59]
	v_mfma_f32_16x16x32_bf16 v[48:51], v[232:235], v[148:151], v[48:51]
	v_mfma_f32_16x16x32_bf16 v[40:43], v[210:213], v[166:169], v[40:43]
	v_mfma_f32_16x16x32_bf16 v[32:35], v[232:235], v[166:169], v[32:35]
	v_mfma_f32_16x16x32_bf16 v[24:27], v[210:213], v[188:191], v[24:27]
	v_mfma_f32_16x16x32_bf16 v[16:19], v[232:235], v[188:191], v[16:19]
	v_mfma_f32_16x16x32_bf16 v[8:11], v[210:213], v[202:205], v[8:11]
	v_mfma_f32_16x16x32_bf16 v[0:3], v[232:235], v[202:205], v[0:3]
	s_add_i32 s28, 0, 0x18000
	v_add_u32_e32 v140, s28, v200
	s_barrier
	ds_read_b128 v[128:131], v140
	ds_read_b128 v[132:135], v140 offset:1024
	ds_read_b128 v[136:139], v140 offset:2048
	ds_read_b128 v[140:143], v140 offset:3072
	s_add_u32 s98, s52, 0x40000
	s_addc_u32 s99, s53, 0
	s_mov_b32 m0, s58
	ds_read_b128 v[144:147], v201 offset:32768
	ds_read_b128 v[152:155], v201 offset:34816
	ds_read_b128 v[170:173], v201 offset:36864
	ds_read_b128 v[192:195], v201 offset:38912
	ds_read_b128 v[148:151], v201 offset:33792
	ds_read_b128 v[166:169], v201 offset:35840
	ds_read_b128 v[188:191], v201 offset:37888
	ds_read_b128 v[202:205], v201 offset:39936
	global_load_lds_dwordx4 v156, s[98:99]
	s_mov_b32 m0, s59
	s_nop 0
	global_load_lds_dwordx4 v158, s[98:99]
	s_waitcnt lgkmcnt(8)
	s_barrier
	s_waitcnt lgkmcnt(7)
	v_mfma_f32_16x16x32_bf16 v[124:127], v[128:131], v[144:147], v[124:127]
	v_mfma_f32_16x16x32_bf16 v[116:119], v[136:139], v[144:147], v[116:119]
	s_waitcnt lgkmcnt(6)
	v_mfma_f32_16x16x32_bf16 v[108:111], v[128:131], v[152:155], v[108:111]
	v_mfma_f32_16x16x32_bf16 v[100:103], v[136:139], v[152:155], v[100:103]
	s_waitcnt lgkmcnt(5)
	v_mfma_f32_16x16x32_bf16 v[92:95], v[128:131], v[170:173], v[92:95]
	v_mfma_f32_16x16x32_bf16 v[84:87], v[136:139], v[170:173], v[84:87]
	s_waitcnt lgkmcnt(4)
	v_mfma_f32_16x16x32_bf16 v[76:79], v[128:131], v[192:195], v[76:79]
	v_mfma_f32_16x16x32_bf16 v[68:71], v[136:139], v[192:195], v[68:71]
	s_waitcnt lgkmcnt(3)
	v_mfma_f32_16x16x32_bf16 v[124:127], v[132:135], v[148:151], v[124:127]
	v_mfma_f32_16x16x32_bf16 v[116:119], v[140:143], v[148:151], v[116:119]
	s_waitcnt lgkmcnt(2)
	v_mfma_f32_16x16x32_bf16 v[108:111], v[132:135], v[166:169], v[108:111]
	v_mfma_f32_16x16x32_bf16 v[100:103], v[140:143], v[166:169], v[100:103]
	s_waitcnt lgkmcnt(1)
	v_mfma_f32_16x16x32_bf16 v[92:95], v[132:135], v[188:191], v[92:95]
	v_mfma_f32_16x16x32_bf16 v[84:87], v[140:143], v[188:191], v[84:87]
	s_waitcnt lgkmcnt(0)
	v_mfma_f32_16x16x32_bf16 v[76:79], v[132:135], v[202:205], v[76:79]
	v_mfma_f32_16x16x32_bf16 v[68:71], v[140:143], v[202:205], v[68:71]
	s_barrier
	s_add_i32 s29, 0, 0x1c000
	s_add_i32 s28, s28, s55
	v_add_u32_e32 v232, s29, v200
	s_add_i32 m0, s28, 0xffffff80
	ds_read_b128 v[206:209], v232
	ds_read_b128 v[210:213], v232 offset:1024
	ds_read_b128 v[214:217], v232 offset:2048
	ds_read_b128 v[232:235], v232 offset:3072
	global_load_lds_dwordx4 v176, s[50:51] offset:128
	s_add_i32 m0, s28, 0x1f80
	s_nop 0
	global_load_lds_dwordx4 v160, s[50:51] offset:128
	s_barrier
	s_waitcnt lgkmcnt(3)
	v_mfma_f32_16x16x32_bf16 v[120:123], v[206:209], v[144:147], v[120:123]
	s_waitcnt lgkmcnt(1)
	v_mfma_f32_16x16x32_bf16 v[112:115], v[214:217], v[144:147], v[112:115]
	v_mfma_f32_16x16x32_bf16 v[104:107], v[206:209], v[152:155], v[104:107]
	v_mfma_f32_16x16x32_bf16 v[96:99], v[214:217], v[152:155], v[96:99]
	v_mfma_f32_16x16x32_bf16 v[88:91], v[206:209], v[170:173], v[88:91]
	v_mfma_f32_16x16x32_bf16 v[80:83], v[214:217], v[170:173], v[80:83]
	v_mfma_f32_16x16x32_bf16 v[72:75], v[206:209], v[192:195], v[72:75]
	v_mfma_f32_16x16x32_bf16 v[64:67], v[214:217], v[192:195], v[64:67]
	v_mfma_f32_16x16x32_bf16 v[120:123], v[210:213], v[148:151], v[120:123]
	s_waitcnt lgkmcnt(0)
	v_mfma_f32_16x16x32_bf16 v[112:115], v[232:235], v[148:151], v[112:115]
	v_mfma_f32_16x16x32_bf16 v[104:107], v[210:213], v[166:169], v[104:107]
	v_mfma_f32_16x16x32_bf16 v[96:99], v[232:235], v[166:169], v[96:99]
	v_mfma_f32_16x16x32_bf16 v[88:91], v[210:213], v[188:191], v[88:91]
	v_mfma_f32_16x16x32_bf16 v[80:83], v[232:235], v[188:191], v[80:83]
	v_mfma_f32_16x16x32_bf16 v[72:75], v[210:213], v[202:205], v[72:75]
	v_mfma_f32_16x16x32_bf16 v[64:67], v[232:235], v[202:205], v[64:67]
	s_add_i32 m0, s62, 0xffffff80
	s_barrier
	ds_read_b128 v[144:147], v201 offset:49152
	ds_read_b128 v[152:155], v201 offset:51200
	ds_read_b128 v[170:173], v201 offset:53248
	ds_read_b128 v[192:195], v201 offset:55296
	ds_read_b128 v[148:151], v201 offset:50176
	ds_read_b128 v[166:169], v201 offset:52224
	ds_read_b128 v[188:191], v201 offset:54272
	ds_read_b128 v[202:205], v201 offset:56320
	global_load_lds_dwordx4 v156, s[52:53] offset:128
	s_add_i32 m0, s63, 0xffffff80
	s_nop 0
	global_load_lds_dwordx4 v158, s[52:53] offset:128
	s_barrier
	s_waitcnt lgkmcnt(7)
	v_mfma_f32_16x16x32_bf16 v[60:63], v[128:131], v[144:147], v[60:63]
	v_mfma_f32_16x16x32_bf16 v[52:55], v[136:139], v[144:147], v[52:55]
	s_waitcnt lgkmcnt(6)
	v_mfma_f32_16x16x32_bf16 v[44:47], v[128:131], v[152:155], v[44:47]
	v_mfma_f32_16x16x32_bf16 v[36:39], v[136:139], v[152:155], v[36:39]
	s_waitcnt lgkmcnt(5)
	v_mfma_f32_16x16x32_bf16 v[28:31], v[128:131], v[170:173], v[28:31]
	v_mfma_f32_16x16x32_bf16 v[20:23], v[136:139], v[170:173], v[20:23]
	s_waitcnt lgkmcnt(4)
	v_mfma_f32_16x16x32_bf16 v[12:15], v[128:131], v[192:195], v[12:15]
	v_mfma_f32_16x16x32_bf16 v[4:7], v[136:139], v[192:195], v[4:7]
	s_waitcnt lgkmcnt(3)
	v_mfma_f32_16x16x32_bf16 v[60:63], v[132:135], v[148:151], v[60:63]
	v_mfma_f32_16x16x32_bf16 v[52:55], v[140:143], v[148:151], v[52:55]
	s_waitcnt lgkmcnt(2)
	v_mfma_f32_16x16x32_bf16 v[44:47], v[132:135], v[166:169], v[44:47]
	v_mfma_f32_16x16x32_bf16 v[36:39], v[140:143], v[166:169], v[36:39]
	s_waitcnt lgkmcnt(1)
	v_mfma_f32_16x16x32_bf16 v[28:31], v[132:135], v[188:191], v[28:31]
	v_mfma_f32_16x16x32_bf16 v[20:23], v[140:143], v[188:191], v[20:23]
	s_waitcnt lgkmcnt(0)
	v_mfma_f32_16x16x32_bf16 v[12:15], v[132:135], v[202:205], v[12:15]
	v_mfma_f32_16x16x32_bf16 v[4:7], v[140:143], v[202:205], v[4:7]
	s_barrier
	s_add_u32 s50, s50, 0x40080
	s_addc_u32 s51, s51, 0
	s_add_i32 s28, s29, s55
	s_mov_b32 m0, s28
	s_nop 0
	global_load_lds_dwordx4 v176, s[50:51]
	s_add_i32 m0, s28, 0x2000
	s_nop 0
	global_load_lds_dwordx4 v160, s[50:51]
	s_waitcnt vmcnt(6)
	s_barrier
	v_mfma_f32_16x16x32_bf16 v[56:59], v[206:209], v[144:147], v[56:59]
	v_mfma_f32_16x16x32_bf16 v[48:51], v[214:217], v[144:147], v[48:51]
	v_mfma_f32_16x16x32_bf16 v[40:43], v[206:209], v[152:155], v[40:43]
	v_mfma_f32_16x16x32_bf16 v[32:35], v[214:217], v[152:155], v[32:35]
	v_mfma_f32_16x16x32_bf16 v[24:27], v[206:209], v[170:173], v[24:27]
	v_mfma_f32_16x16x32_bf16 v[16:19], v[214:217], v[170:173], v[16:19]
	v_mfma_f32_16x16x32_bf16 v[8:11], v[206:209], v[192:195], v[8:11]
	v_mfma_f32_16x16x32_bf16 v[0:3], v[214:217], v[192:195], v[0:3]
	v_mfma_f32_16x16x32_bf16 v[56:59], v[210:213], v[148:151], v[56:59]
	v_mfma_f32_16x16x32_bf16 v[48:51], v[232:235], v[148:151], v[48:51]
	v_mfma_f32_16x16x32_bf16 v[40:43], v[210:213], v[166:169], v[40:43]
	v_mfma_f32_16x16x32_bf16 v[32:35], v[232:235], v[166:169], v[32:35]
	v_mfma_f32_16x16x32_bf16 v[24:27], v[210:213], v[188:191], v[24:27]
	v_mfma_f32_16x16x32_bf16 v[16:19], v[232:235], v[188:191], v[16:19]
	v_mfma_f32_16x16x32_bf16 v[8:11], v[210:213], v[202:205], v[8:11]
	v_mfma_f32_16x16x32_bf16 v[0:3], v[232:235], v[202:205], v[0:3]
	s_add_i32 s70, s70, 2
	s_add_u32 s6, s6, 0x100
	s_addc_u32 s7, s7, 0
	s_add_u32 s68, s68, 0x100
	s_addc_u32 s69, s69, 0
	s_cmp_lt_u32 s70, 14
	s_barrier
	s_cbranch_scc1 .LBB0_1436
	v_mov_b32_e32 v134, v199
	v_mov_b32_e32 v128, v198
	s_lshl_b32 s4, s4, 8
	s_add_i32 s4, s4, s60
	v_add_u32_e32 v192, s4, v128
	v_lshlrev_b32_e32 v128, 2, v134
	v_ashrrev_i32_e32 v129, 31, v128
	v_ashrrev_i32_e32 v193, 31, v192
	v_add_u32_e32 v190, 16, v192
	v_lshl_add_u64 v[132:133], v[128:129], 2, s[8:9]
	v_lshlrev_b64 v[128:129], 6, v[192:193]
	v_ashrrev_i32_e32 v191, 31, v190
	v_add_u32_e32 v188, 32, v192
	v_lshl_add_u64 v[128:129], v[132:133], 0, v[128:129]
	v_lshlrev_b64 v[130:131], 6, v[190:191]
	v_ashrrev_i32_e32 v189, 31, v188
	v_lshl_add_u64 v[130:131], v[132:133], 0, v[130:131]
	global_load_dwordx4 v[202:205], v[128:129], off
	global_load_dwordx4 v[144:147], v[130:131], off
	v_lshlrev_b64 v[128:129], 6, v[188:189]
	v_add_u32_e32 v174, 48, v192
	v_lshl_add_u64 v[128:129], v[132:133], 0, v[128:129]
	v_ashrrev_i32_e32 v175, 31, v174
	global_load_dwordx4 v[148:151], v[128:129], off
	v_lshlrev_b64 v[128:129], 6, v[174:175]
	v_lshl_add_u64 v[128:129], v[132:133], 0, v[128:129]
	global_load_dwordx4 v[152:155], v[128:129], off
	v_add_u32_e32 v172, 0x80, v192
	v_ashrrev_i32_e32 v173, 31, v172
	v_lshlrev_b64 v[128:129], 6, v[172:173]
	v_lshl_add_u64 v[128:129], v[132:133], 0, v[128:129]
	global_load_dwordx4 v[140:143], v[128:129], off
	v_add_u32_e32 v170, 0x90, v192
	v_ashrrev_i32_e32 v171, 31, v170
	v_lshlrev_b64 v[128:129], 6, v[170:171]
	v_lshl_add_u64 v[128:129], v[132:133], 0, v[128:129]
	global_load_dwordx4 v[128:131], v[128:129], off
	s_lshl_b32 s5, s5, 7
	v_add_u32_e32 v168, 0xa0, v192
	v_add_u32_e32 v166, 0xb0, v192
	s_or_b32 s5, s5, s61
	v_ashrrev_i32_e32 v169, 31, v168
	v_ashrrev_i32_e32 v167, 31, v166
	v_lshl_add_u32 v194, v134, 3, s5
	v_lshlrev_b64 v[134:135], 6, v[168:169]
	v_lshlrev_b64 v[136:137], 6, v[166:167]
	v_lshl_add_u64 v[134:135], v[132:133], 0, v[134:135]
	v_lshl_add_u64 v[132:133], v[132:133], 0, v[136:137]
	global_load_dwordx4 v[136:139], v[134:135], off
	s_nop 0
	global_load_dwordx4 v[132:135], v[132:133], off
	s_mov_b32 s4, 0x358637bd
	v_mov_b64_e32 v[196:197], s[4:5]
	v_ashrrev_i32_e32 v195, 31, v194
	s_mov_b64 s[50:51], s[20:21]
	s_waitcnt vmcnt(0)
	v_mov_b32_e32 v206, v203
	v_mov_b32_e32 v207, v204
	v_mov_b32_e32 v203, v205
	v_mov_b32_e32 v204, v145
	v_mov_b32_e32 v205, v146
	v_mov_b32_e32 v145, v147
	v_pk_add_f32 v[202:203], v[206:207], v[202:203]
	v_mov_b32_e32 v146, v149
	v_mov_b32_e32 v147, v150
	v_mov_b32_e32 v149, v151
	v_mov_b32_e32 v150, v153
	v_mov_b32_e32 v151, v154
	v_mov_b32_e32 v153, v155
	v_pk_add_f32 v[144:145], v[204:205], v[144:145]
	v_mov_b32_e32 v155, v202
	v_pk_add_f32 v[146:147], v[146:147], v[148:149]
	v_pk_add_f32 v[148:149], v[150:151], v[152:153]
	v_mov_b32_e32 v154, v144
	v_mov_b32_e32 v202, v145
	v_mov_b32_e32 v144, v148
	v_mov_b32_e32 v145, v146
	v_mov_b32_e32 v146, v149
	v_pk_add_f32 v[148:149], v[154:155], v[202:203]
	v_pk_add_f32 v[144:145], v[144:145], v[146:147]
	ds_bpermute_b32 v147, v219, v149
	ds_bpermute_b32 v146, v219, v148
	ds_bpermute_b32 v151, v219, v145
	ds_bpermute_b32 v150, v219, v144
	v_mov_b32_e32 v152, v141
	v_mov_b32_e32 v153, v142
	v_mov_b32_e32 v141, v143
	s_waitcnt lgkmcnt(0)
	v_pk_add_f32 v[142:143], v[148:149], v[146:147]
	ds_bpermute_b32 v147, v218, v143
	ds_bpermute_b32 v146, v218, v142
	v_pk_add_f32 v[144:145], v[144:145], v[150:151]
	ds_bpermute_b32 v149, v218, v145
	ds_bpermute_b32 v148, v218, v144
	v_mov_b32_e32 v150, v129
	s_waitcnt lgkmcnt(2)
	v_pk_add_f32 v[142:143], v[142:143], v[146:147]
	v_mov_b32_e32 v151, v130
	v_pk_fma_f32 v[142:143], v[142:143], s[30:31], v[196:197] op_sel_hi:[1,0,0]
	s_waitcnt lgkmcnt(0)
	v_pk_add_f32 v[144:145], v[144:145], v[148:149]
	v_mul_f32_e32 v129, 0x4b800000, v143
	v_cmp_gt_f32_e32 vcc, s86, v143
	v_pk_fma_f32 v[146:147], v[144:145], s[30:31], v[196:197] op_sel_hi:[1,0,0]
	v_mul_f32_e32 v130, 0x4b800000, v142
	v_cndmask_b32_e32 v129, v143, v129, vcc
	v_rsq_f32_e32 v129, v129
	v_cmp_gt_f32_e64 s[4:5], s86, v142
	v_mul_f32_e32 v144, 0x4b800000, v147
	v_cmp_gt_f32_e64 s[6:7], s86, v147
	v_cndmask_b32_e64 v130, v142, v130, s[4:5]
	v_rsq_f32_e32 v142, v130
	v_cndmask_b32_e64 v130, v147, v144, s[6:7]
	v_rsq_f32_e32 v143, v130
	v_mul_f32_e32 v130, 0x45800000, v129
	v_cndmask_b32_e32 v144, v129, v130, vcc
	v_mov_b32_e32 v129, v131
	v_pk_add_f32 v[140:141], v[152:153], v[140:141]
	v_pk_add_f32 v[128:129], v[150:151], v[128:129]
	v_mov_b32_e32 v131, v140
	v_mov_b32_e32 v130, v128
	v_mov_b32_e32 v140, v129
	v_pk_add_f32 v[128:129], v[130:131], v[140:141]
	ds_bpermute_b32 v131, v219, v129
	ds_bpermute_b32 v130, v219, v128
	v_mul_f32_e32 v145, 0x45800000, v142
	v_cndmask_b32_e64 v142, v142, v145, s[4:5]
	v_mul_f32_e32 v140, 0x4b800000, v146
	v_cmp_gt_f32_e32 vcc, s86, v146
	s_waitcnt lgkmcnt(0)
	v_pk_add_f32 v[128:129], v[128:129], v[130:131]
	ds_bpermute_b32 v131, v218, v129
	ds_bpermute_b32 v130, v218, v128
	v_cndmask_b32_e32 v140, v146, v140, vcc
	v_rsq_f32_e32 v141, v140
	v_mul_f32_e32 v140, 0x45800000, v143
	v_cndmask_b32_e64 v140, v143, v140, s[6:7]
	s_waitcnt lgkmcnt(0)
	v_pk_add_f32 v[128:129], v[128:129], v[130:131]
	v_mov_b32_e32 v131, v138
	v_pk_fma_f32 v[128:129], v[128:129], s[30:31], v[196:197] op_sel_hi:[1,0,0]
	v_mul_f32_e32 v143, 0x45800000, v141
	v_mul_f32_e32 v130, 0x4b800000, v129
	v_cmp_gt_f32_e64 s[4:5], s86, v129
	v_cmp_gt_f32_e64 s[6:7], s86, v128
	v_pk_mul_f32 v[110:111], v[110:111], v[142:143] op_sel_hi:[1,0]
	v_cndmask_b32_e64 v129, v129, v130, s[4:5]
	v_mov_b32_e32 v130, v137
	v_mov_b32_e32 v137, v139
	v_pk_add_f32 v[130:131], v[130:131], v[136:137]
	v_mov_b32_e32 v136, v133
	v_mov_b32_e32 v137, v134
	v_mov_b32_e32 v133, v135
	v_pk_add_f32 v[132:133], v[136:137], v[132:133]
	v_mov_b32_e32 v135, v130
	v_mov_b32_e32 v134, v132
	v_mov_b32_e32 v130, v133
	v_pk_add_f32 v[130:131], v[134:135], v[130:131]
	ds_bpermute_b32 v133, v219, v131
	ds_bpermute_b32 v132, v219, v130
	v_rsq_f32_e32 v145, v129
	v_mul_f32_e32 v129, 0x4b800000, v128
	v_cndmask_b32_e64 v128, v128, v129, s[6:7]
	v_rsq_f32_e32 v135, v128
	s_waitcnt lgkmcnt(0)
	v_pk_add_f32 v[128:129], v[130:131], v[132:133]
	ds_bpermute_b32 v131, v218, v129
	ds_bpermute_b32 v130, v218, v128
	v_pk_mul_f32 v[126:127], v[126:127], v[144:145] op_sel_hi:[1,0]
	v_pk_mul_f32 v[122:123], v[122:123], v[144:145] op_sel_hi:[1,0]
	v_pk_mul_f32 v[116:117], v[116:117], v[144:145] op_sel_hi:[1,0]
	v_pk_mul_f32 v[124:125], v[124:125], v[144:145] op_sel_hi:[1,0]
	v_pk_mul_f32 v[138:139], v[126:127], s[44:45] op_sel_hi:[1,0]
	v_pk_mul_f32 v[120:121], v[120:121], v[144:145] op_sel_hi:[1,0]
	v_pk_mul_f32 v[122:123], v[126:127], v[122:123]
	v_pk_mul_f32 v[118:119], v[118:119], v[144:145] op_sel_hi:[1,0]
	v_pk_mul_f32 v[126:127], v[116:117], s[44:45] op_sel_hi:[1,0]
	v_pk_mul_f32 v[146:147], v[124:125], s[44:45] op_sel_hi:[1,0]
	v_pk_mul_f32 v[120:121], v[124:125], v[120:121]
	v_pk_mul_f32 v[124:125], v[118:119], s[44:45] op_sel_hi:[1,0]
	v_exp_f32_e32 v126, v126
	v_exp_f32_e32 v127, v127
	s_waitcnt lgkmcnt(0)
	v_pk_add_f32 v[128:129], v[128:129], v[130:131]
	v_exp_f32_e32 v146, v146
	v_exp_f32_e32 v138, v138
	v_exp_f32_e32 v139, v139
	v_exp_f32_e32 v147, v147
	v_exp_f32_e32 v124, v124
	v_exp_f32_e32 v125, v125
	v_pk_fma_f32 v[128:129], v[128:129], s[30:31], v[196:197] op_sel_hi:[1,0,0]
	v_cndmask_b32_e32 v136, v141, v143, vcc
	v_mul_f32_e32 v132, 0x45800000, v145
	v_mul_f32_e32 v130, 0x4b800000, v129
	v_cmp_gt_f32_e32 vcc, s86, v129
	v_cndmask_b32_e64 v134, v145, v132, s[4:5]
	v_cmp_gt_f32_e64 s[4:5], s86, v128
	v_cndmask_b32_e32 v129, v129, v130, vcc
	v_mul_f32_e32 v130, 0x4b800000, v128
	v_pk_add_f32 v[126:127], v[126:127], 1.0 op_sel_hi:[1,0]
	v_rsq_f32_e32 v129, v129
	v_cndmask_b32_e64 v128, v128, v130, s[4:5]
	v_pk_add_f32 v[138:139], v[138:139], 1.0 op_sel_hi:[1,0]
	v_pk_add_f32 v[146:147], v[146:147], 1.0 op_sel_hi:[1,0]
	v_pk_add_f32 v[124:125], v[124:125], 1.0 op_sel_hi:[1,0]
	v_rcp_f32_e32 v126, v126
	v_rcp_f32_e32 v127, v127
	v_rsq_f32_e32 v128, v128
	v_rcp_f32_e32 v146, v146
	v_rcp_f32_e32 v138, v138
	v_rcp_f32_e32 v139, v139
	v_rcp_f32_e32 v147, v147
	v_rcp_f32_e32 v124, v124
	v_rcp_f32_e32 v125, v125
	v_pk_mul_f32 v[112:113], v[112:113], v[144:145] op_sel_hi:[1,0]
	v_pk_mul_f32 v[114:115], v[114:115], v[144:145] op_sel_hi:[1,0]
	v_pk_mul_f32 v[112:113], v[116:117], v[112:113]
	v_mul_f32_e32 v130, 0x45800000, v129
	v_pk_mul_f32 v[114:115], v[118:119], v[114:115]
	v_pk_mul_f32 v[112:113], v[112:113], v[126:127]
	v_cndmask_b32_e32 v130, v129, v130, vcc
	v_mul_f32_e32 v129, 0x45800000, v128
	v_pk_mul_f32 v[122:123], v[122:123], v[138:139]
	v_pk_mul_f32 v[120:121], v[120:121], v[146:147]
	v_pk_mul_f32 v[114:115], v[114:115], v[124:125]
	v_cvt_pk_bf16_f32 v116, v120, v121
	v_cvt_pk_bf16_f32 v117, v122, v123
	v_cvt_pk_bf16_f32 v118, v112, v113
	v_mov_b64_e32 v[112:113], s[10:11]
	v_cndmask_b32_e64 v128, v128, v129, s[4:5]
	v_cvt_pk_bf16_f32 v119, v114, v115
	v_mad_i64_i32 v[120:121], s[4:5], v192, s35, v[112:113]
	v_lshlrev_b64 v[114:115], 1, v[194:195]
	v_lshl_add_u64 v[120:121], v[120:121], 0, v[114:115]
	v_pk_mul_f32 v[108:109], v[108:109], v[142:143] op_sel_hi:[1,0]
	v_pk_mul_f32 v[106:107], v[106:107], v[142:143] op_sel_hi:[1,0]
	v_pk_mul_f32 v[104:105], v[104:105], v[142:143] op_sel_hi:[1,0]
	v_pk_mul_f32 v[102:103], v[102:103], v[142:143] op_sel_hi:[1,0]
	v_pk_mul_f32 v[100:101], v[100:101], v[142:143] op_sel_hi:[1,0]
	global_store_dwordx4 v[120:121], v[116:119], off
	v_pk_mul_f32 v[104:105], v[108:109], v[104:105]
	v_pk_mul_f32 v[106:107], v[110:111], v[106:107]
	v_pk_mul_f32 v[116:117], v[110:111], s[44:45] op_sel_hi:[1,0]
	v_pk_mul_f32 v[118:119], v[108:109], s[44:45] op_sel_hi:[1,0]
	v_pk_mul_f32 v[108:109], v[102:103], s[44:45] op_sel_hi:[1,0]
	v_pk_mul_f32 v[110:111], v[100:101], s[44:45] op_sel_hi:[1,0]
	v_exp_f32_e32 v108, v108
	v_exp_f32_e32 v110, v110
	v_exp_f32_e32 v109, v109
	v_exp_f32_e32 v111, v111
	v_exp_f32_e32 v118, v118
	v_exp_f32_e32 v116, v116
	v_exp_f32_e32 v117, v117
	v_exp_f32_e32 v119, v119
	v_pk_add_f32 v[108:109], v[108:109], 1.0 op_sel_hi:[1,0]
	v_pk_add_f32 v[110:111], v[110:111], 1.0 op_sel_hi:[1,0]
	v_pk_add_f32 v[116:117], v[116:117], 1.0 op_sel_hi:[1,0]
	v_pk_add_f32 v[118:119], v[118:119], 1.0 op_sel_hi:[1,0]
	v_rcp_f32_e32 v110, v110
	v_rcp_f32_e32 v108, v108
	v_rcp_f32_e32 v109, v109
	v_rcp_f32_e32 v111, v111
	v_rcp_f32_e32 v118, v118
	v_rcp_f32_e32 v116, v116
	v_rcp_f32_e32 v117, v117
	v_rcp_f32_e32 v119, v119
	v_pk_mul_f32 v[98:99], v[98:99], v[142:143] op_sel_hi:[1,0]
	v_pk_mul_f32 v[96:97], v[96:97], v[142:143] op_sel_hi:[1,0]
	v_pk_mul_f32 v[98:99], v[102:103], v[98:99]
	v_pk_mul_f32 v[96:97], v[100:101], v[96:97]
	v_pk_mul_f32 v[100:101], v[98:99], v[108:109]
	v_pk_mul_f32 v[98:99], v[96:97], v[110:111]
	v_pk_mul_f32 v[106:107], v[106:107], v[116:117]
	v_pk_mul_f32 v[104:105], v[104:105], v[118:119]
	v_pk_mul_f32 v[94:95], v[94:95], v[140:141] op_sel_hi:[1,0]
	v_cvt_pk_bf16_f32 v96, v104, v105
	v_cvt_pk_bf16_f32 v97, v106, v107
	v_cvt_pk_bf16_f32 v98, v98, v99
	v_cvt_pk_bf16_f32 v99, v100, v101
	v_mad_i64_i32 v[100:101], s[4:5], v190, s35, v[112:113]
	v_lshl_add_u64 v[100:101], v[100:101], 0, v[114:115]
	v_pk_mul_f32 v[92:93], v[92:93], v[140:141] op_sel_hi:[1,0]
	v_pk_mul_f32 v[90:91], v[90:91], v[140:141] op_sel_hi:[1,0]
	v_pk_mul_f32 v[88:89], v[88:89], v[140:141] op_sel_hi:[1,0]
	v_pk_mul_f32 v[86:87], v[86:87], v[140:141] op_sel_hi:[1,0]
	v_pk_mul_f32 v[84:85], v[84:85], v[140:141] op_sel_hi:[1,0]
	global_store_dwordx4 v[100:101], v[96:99], off
	v_pk_mul_f32 v[88:89], v[92:93], v[88:89]
	v_pk_mul_f32 v[90:91], v[94:95], v[90:91]
	v_pk_mul_f32 v[96:97], v[94:95], s[44:45] op_sel_hi:[1,0]
	v_pk_mul_f32 v[98:99], v[92:93], s[44:45] op_sel_hi:[1,0]
	v_pk_mul_f32 v[92:93], v[86:87], s[44:45] op_sel_hi:[1,0]
	v_pk_mul_f32 v[94:95], v[84:85], s[44:45] op_sel_hi:[1,0]
	v_exp_f32_e32 v92, v92
	v_exp_f32_e32 v94, v94
	v_exp_f32_e32 v93, v93
	v_exp_f32_e32 v95, v95
	v_exp_f32_e32 v98, v98
	v_exp_f32_e32 v96, v96
	v_exp_f32_e32 v97, v97
	v_exp_f32_e32 v99, v99
	v_pk_add_f32 v[92:93], v[92:93], 1.0 op_sel_hi:[1,0]
	v_pk_add_f32 v[94:95], v[94:95], 1.0 op_sel_hi:[1,0]
	v_pk_add_f32 v[96:97], v[96:97], 1.0 op_sel_hi:[1,0]
	v_pk_add_f32 v[98:99], v[98:99], 1.0 op_sel_hi:[1,0]
	v_rcp_f32_e32 v94, v94
	v_rcp_f32_e32 v92, v92
	v_rcp_f32_e32 v93, v93
	v_rcp_f32_e32 v95, v95
	v_rcp_f32_e32 v98, v98
	v_rcp_f32_e32 v96, v96
	v_rcp_f32_e32 v97, v97
	v_rcp_f32_e32 v99, v99
	v_pk_mul_f32 v[82:83], v[82:83], v[140:141] op_sel_hi:[1,0]
	v_pk_mul_f32 v[80:81], v[80:81], v[140:141] op_sel_hi:[1,0]
	v_pk_mul_f32 v[82:83], v[86:87], v[82:83]
	v_pk_mul_f32 v[80:81], v[84:85], v[80:81]
	v_pk_mul_f32 v[84:85], v[82:83], v[92:93]
	v_pk_mul_f32 v[82:83], v[80:81], v[94:95]
	v_pk_mul_f32 v[90:91], v[90:91], v[96:97]
	v_pk_mul_f32 v[88:89], v[88:89], v[98:99]
	v_pk_mul_f32 v[78:79], v[78:79], v[136:137] op_sel_hi:[1,0]
	v_cvt_pk_bf16_f32 v80, v88, v89
	v_cvt_pk_bf16_f32 v81, v90, v91
	v_cvt_pk_bf16_f32 v82, v82, v83
	v_cvt_pk_bf16_f32 v83, v84, v85
	v_mad_i64_i32 v[84:85], s[4:5], v188, s35, v[112:113]
	v_lshl_add_u64 v[84:85], v[84:85], 0, v[114:115]
	v_pk_mul_f32 v[76:77], v[76:77], v[136:137] op_sel_hi:[1,0]
	v_pk_mul_f32 v[74:75], v[74:75], v[136:137] op_sel_hi:[1,0]
	v_pk_mul_f32 v[72:73], v[72:73], v[136:137] op_sel_hi:[1,0]
	v_pk_mul_f32 v[70:71], v[70:71], v[136:137] op_sel_hi:[1,0]
	v_pk_mul_f32 v[68:69], v[68:69], v[136:137] op_sel_hi:[1,0]
	global_store_dwordx4 v[84:85], v[80:83], off
	v_pk_mul_f32 v[72:73], v[76:77], v[72:73]
	v_pk_mul_f32 v[74:75], v[78:79], v[74:75]
	v_pk_mul_f32 v[80:81], v[78:79], s[44:45] op_sel_hi:[1,0]
	v_pk_mul_f32 v[82:83], v[76:77], s[44:45] op_sel_hi:[1,0]
	v_pk_mul_f32 v[76:77], v[70:71], s[44:45] op_sel_hi:[1,0]
	v_pk_mul_f32 v[78:79], v[68:69], s[44:45] op_sel_hi:[1,0]
	v_exp_f32_e32 v76, v76
	v_exp_f32_e32 v78, v78
	v_exp_f32_e32 v77, v77
	v_exp_f32_e32 v79, v79
	v_exp_f32_e32 v82, v82
	v_exp_f32_e32 v80, v80
	v_exp_f32_e32 v81, v81
	v_exp_f32_e32 v83, v83
	v_pk_add_f32 v[76:77], v[76:77], 1.0 op_sel_hi:[1,0]
	v_pk_add_f32 v[78:79], v[78:79], 1.0 op_sel_hi:[1,0]
	v_pk_add_f32 v[80:81], v[80:81], 1.0 op_sel_hi:[1,0]
	v_pk_add_f32 v[82:83], v[82:83], 1.0 op_sel_hi:[1,0]
	v_rcp_f32_e32 v78, v78
	v_rcp_f32_e32 v76, v76
	v_rcp_f32_e32 v77, v77
	v_rcp_f32_e32 v79, v79
	v_rcp_f32_e32 v82, v82
	v_rcp_f32_e32 v80, v80
	v_rcp_f32_e32 v81, v81
	v_rcp_f32_e32 v83, v83
	v_pk_mul_f32 v[66:67], v[66:67], v[136:137] op_sel_hi:[1,0]
	v_pk_mul_f32 v[64:65], v[64:65], v[136:137] op_sel_hi:[1,0]
	v_pk_mul_f32 v[66:67], v[70:71], v[66:67]
	v_pk_mul_f32 v[64:65], v[68:69], v[64:65]
	v_pk_mul_f32 v[68:69], v[66:67], v[76:77]
	v_pk_mul_f32 v[66:67], v[64:65], v[78:79]
	v_pk_mul_f32 v[74:75], v[74:75], v[80:81]
	v_pk_mul_f32 v[72:73], v[72:73], v[82:83]
	v_pk_mul_f32 v[62:63], v[62:63], v[134:135] op_sel_hi:[1,0]
	v_cvt_pk_bf16_f32 v64, v72, v73
	v_cvt_pk_bf16_f32 v65, v74, v75
	v_cvt_pk_bf16_f32 v66, v66, v67
	v_cvt_pk_bf16_f32 v67, v68, v69
	v_mad_i64_i32 v[68:69], s[4:5], v174, s35, v[112:113]
	v_lshl_add_u64 v[68:69], v[68:69], 0, v[114:115]
	v_pk_mul_f32 v[60:61], v[60:61], v[134:135] op_sel_hi:[1,0]
	v_pk_mul_f32 v[58:59], v[58:59], v[134:135] op_sel_hi:[1,0]
	v_pk_mul_f32 v[56:57], v[56:57], v[134:135] op_sel_hi:[1,0]
	v_pk_mul_f32 v[54:55], v[54:55], v[134:135] op_sel_hi:[1,0]
	v_pk_mul_f32 v[52:53], v[52:53], v[134:135] op_sel_hi:[1,0]
	global_store_dwordx4 v[68:69], v[64:67], off
	v_pk_mul_f32 v[56:57], v[60:61], v[56:57]
	v_pk_mul_f32 v[58:59], v[62:63], v[58:59]
	v_pk_mul_f32 v[64:65], v[62:63], s[44:45] op_sel_hi:[1,0]
	v_pk_mul_f32 v[66:67], v[60:61], s[44:45] op_sel_hi:[1,0]
	v_pk_mul_f32 v[60:61], v[54:55], s[44:45] op_sel_hi:[1,0]
	v_pk_mul_f32 v[62:63], v[52:53], s[44:45] op_sel_hi:[1,0]
	v_exp_f32_e32 v60, v60
	v_exp_f32_e32 v62, v62
	v_exp_f32_e32 v61, v61
	v_exp_f32_e32 v63, v63
	v_exp_f32_e32 v66, v66
	v_exp_f32_e32 v64, v64
	v_exp_f32_e32 v65, v65
	v_exp_f32_e32 v67, v67
	v_pk_add_f32 v[60:61], v[60:61], 1.0 op_sel_hi:[1,0]
	v_pk_add_f32 v[62:63], v[62:63], 1.0 op_sel_hi:[1,0]
	v_pk_add_f32 v[64:65], v[64:65], 1.0 op_sel_hi:[1,0]
	v_pk_add_f32 v[66:67], v[66:67], 1.0 op_sel_hi:[1,0]
	v_rcp_f32_e32 v62, v62
	v_rcp_f32_e32 v60, v60
	v_rcp_f32_e32 v61, v61
	v_rcp_f32_e32 v63, v63
	v_rcp_f32_e32 v66, v66
	v_rcp_f32_e32 v64, v64
	v_rcp_f32_e32 v65, v65
	v_rcp_f32_e32 v67, v67
	v_pk_mul_f32 v[50:51], v[50:51], v[134:135] op_sel_hi:[1,0]
	v_pk_mul_f32 v[48:49], v[48:49], v[134:135] op_sel_hi:[1,0]
	v_pk_mul_f32 v[50:51], v[54:55], v[50:51]
	v_pk_mul_f32 v[48:49], v[52:53], v[48:49]
	v_mul_f32_e32 v132, 0x45800000, v135
	v_pk_mul_f32 v[52:53], v[50:51], v[60:61]
	v_pk_mul_f32 v[50:51], v[48:49], v[62:63]
	v_cndmask_b32_e64 v132, v135, v132, s[6:7]
	v_pk_mul_f32 v[58:59], v[58:59], v[64:65]
	v_pk_mul_f32 v[56:57], v[56:57], v[66:67]
	v_pk_mul_f32 v[46:47], v[46:47], v[132:133] op_sel_hi:[1,0]
	v_cvt_pk_bf16_f32 v48, v56, v57
	v_cvt_pk_bf16_f32 v49, v58, v59
	v_cvt_pk_bf16_f32 v50, v50, v51
	v_cvt_pk_bf16_f32 v51, v52, v53
	v_mad_i64_i32 v[52:53], s[4:5], v172, s35, v[112:113]
	v_lshl_add_u64 v[52:53], v[52:53], 0, v[114:115]
	v_pk_mul_f32 v[44:45], v[44:45], v[132:133] op_sel_hi:[1,0]
	v_pk_mul_f32 v[42:43], v[42:43], v[132:133] op_sel_hi:[1,0]
	v_pk_mul_f32 v[40:41], v[40:41], v[132:133] op_sel_hi:[1,0]
	v_pk_mul_f32 v[38:39], v[38:39], v[132:133] op_sel_hi:[1,0]
	v_pk_mul_f32 v[36:37], v[36:37], v[132:133] op_sel_hi:[1,0]
	global_store_dwordx4 v[52:53], v[48:51], off
	v_pk_mul_f32 v[40:41], v[44:45], v[40:41]
	v_pk_mul_f32 v[42:43], v[46:47], v[42:43]
	v_pk_mul_f32 v[48:49], v[46:47], s[44:45] op_sel_hi:[1,0]
	v_pk_mul_f32 v[50:51], v[44:45], s[44:45] op_sel_hi:[1,0]
	v_pk_mul_f32 v[44:45], v[38:39], s[44:45] op_sel_hi:[1,0]
	v_pk_mul_f32 v[46:47], v[36:37], s[44:45] op_sel_hi:[1,0]
	v_exp_f32_e32 v44, v44
	v_exp_f32_e32 v46, v46
	v_exp_f32_e32 v45, v45
	v_exp_f32_e32 v47, v47
	v_exp_f32_e32 v50, v50
	v_exp_f32_e32 v48, v48
	v_exp_f32_e32 v49, v49
	v_exp_f32_e32 v51, v51
	v_pk_add_f32 v[44:45], v[44:45], 1.0 op_sel_hi:[1,0]
	v_pk_add_f32 v[46:47], v[46:47], 1.0 op_sel_hi:[1,0]
	v_pk_add_f32 v[48:49], v[48:49], 1.0 op_sel_hi:[1,0]
	v_pk_add_f32 v[50:51], v[50:51], 1.0 op_sel_hi:[1,0]
	v_rcp_f32_e32 v46, v46
	v_rcp_f32_e32 v44, v44
	v_rcp_f32_e32 v45, v45
	v_rcp_f32_e32 v47, v47
	v_rcp_f32_e32 v50, v50
	v_rcp_f32_e32 v48, v48
	v_rcp_f32_e32 v49, v49
	v_rcp_f32_e32 v51, v51
	v_pk_mul_f32 v[34:35], v[34:35], v[132:133] op_sel_hi:[1,0]
	v_pk_mul_f32 v[32:33], v[32:33], v[132:133] op_sel_hi:[1,0]
	v_pk_mul_f32 v[34:35], v[38:39], v[34:35]
	v_pk_mul_f32 v[32:33], v[36:37], v[32:33]
	v_pk_mul_f32 v[36:37], v[34:35], v[44:45]
	v_pk_mul_f32 v[34:35], v[32:33], v[46:47]
	v_pk_mul_f32 v[42:43], v[42:43], v[48:49]
	v_pk_mul_f32 v[40:41], v[40:41], v[50:51]
	v_pk_mul_f32 v[30:31], v[30:31], v[130:131] op_sel_hi:[1,0]
	v_cvt_pk_bf16_f32 v32, v40, v41
	v_cvt_pk_bf16_f32 v33, v42, v43
	v_cvt_pk_bf16_f32 v34, v34, v35
	v_cvt_pk_bf16_f32 v35, v36, v37
	v_mad_i64_i32 v[36:37], s[4:5], v170, s35, v[112:113]
	v_lshl_add_u64 v[36:37], v[36:37], 0, v[114:115]
	v_pk_mul_f32 v[28:29], v[28:29], v[130:131] op_sel_hi:[1,0]
	v_pk_mul_f32 v[26:27], v[26:27], v[130:131] op_sel_hi:[1,0]
	v_pk_mul_f32 v[24:25], v[24:25], v[130:131] op_sel_hi:[1,0]
	v_pk_mul_f32 v[22:23], v[22:23], v[130:131] op_sel_hi:[1,0]
	v_pk_mul_f32 v[20:21], v[20:21], v[130:131] op_sel_hi:[1,0]
	global_store_dwordx4 v[36:37], v[32:35], off
	v_pk_mul_f32 v[24:25], v[28:29], v[24:25]
	v_pk_mul_f32 v[26:27], v[30:31], v[26:27]
	v_pk_mul_f32 v[32:33], v[30:31], s[44:45] op_sel_hi:[1,0]
	v_pk_mul_f32 v[34:35], v[28:29], s[44:45] op_sel_hi:[1,0]
	v_pk_mul_f32 v[28:29], v[22:23], s[44:45] op_sel_hi:[1,0]
	v_pk_mul_f32 v[30:31], v[20:21], s[44:45] op_sel_hi:[1,0]
	v_exp_f32_e32 v28, v28
	v_exp_f32_e32 v30, v30
	v_exp_f32_e32 v29, v29
	v_exp_f32_e32 v31, v31
	v_exp_f32_e32 v34, v34
	v_exp_f32_e32 v32, v32
	v_exp_f32_e32 v33, v33
	v_exp_f32_e32 v35, v35
	v_pk_add_f32 v[28:29], v[28:29], 1.0 op_sel_hi:[1,0]
	v_pk_add_f32 v[30:31], v[30:31], 1.0 op_sel_hi:[1,0]
	v_pk_add_f32 v[32:33], v[32:33], 1.0 op_sel_hi:[1,0]
	v_pk_add_f32 v[34:35], v[34:35], 1.0 op_sel_hi:[1,0]
	v_rcp_f32_e32 v30, v30
	v_rcp_f32_e32 v28, v28
	v_rcp_f32_e32 v29, v29
	v_rcp_f32_e32 v31, v31
	v_rcp_f32_e32 v34, v34
	v_rcp_f32_e32 v32, v32
	v_rcp_f32_e32 v33, v33
	v_rcp_f32_e32 v35, v35
	v_pk_mul_f32 v[18:19], v[18:19], v[130:131] op_sel_hi:[1,0]
	v_pk_mul_f32 v[16:17], v[16:17], v[130:131] op_sel_hi:[1,0]
	v_pk_mul_f32 v[18:19], v[22:23], v[18:19]
	v_pk_mul_f32 v[16:17], v[20:21], v[16:17]
	v_pk_mul_f32 v[20:21], v[18:19], v[28:29]
	v_pk_mul_f32 v[18:19], v[16:17], v[30:31]
	v_pk_mul_f32 v[26:27], v[26:27], v[32:33]
	v_pk_mul_f32 v[24:25], v[24:25], v[34:35]
	v_pk_mul_f32 v[14:15], v[14:15], v[128:129] op_sel_hi:[1,0]
	v_cvt_pk_bf16_f32 v16, v24, v25
	v_cvt_pk_bf16_f32 v17, v26, v27
	v_cvt_pk_bf16_f32 v18, v18, v19
	v_cvt_pk_bf16_f32 v19, v20, v21
	v_mad_i64_i32 v[20:21], s[4:5], v168, s35, v[112:113]
	v_lshl_add_u64 v[20:21], v[20:21], 0, v[114:115]
	v_pk_mul_f32 v[12:13], v[12:13], v[128:129] op_sel_hi:[1,0]
	v_pk_mul_f32 v[10:11], v[10:11], v[128:129] op_sel_hi:[1,0]
	v_pk_mul_f32 v[8:9], v[8:9], v[128:129] op_sel_hi:[1,0]
	v_pk_mul_f32 v[6:7], v[6:7], v[128:129] op_sel_hi:[1,0]
	v_pk_mul_f32 v[4:5], v[4:5], v[128:129] op_sel_hi:[1,0]
	global_store_dwordx4 v[20:21], v[16:19], off
	v_pk_mul_f32 v[8:9], v[12:13], v[8:9]
	v_pk_mul_f32 v[10:11], v[14:15], v[10:11]
	v_pk_mul_f32 v[16:17], v[14:15], s[44:45] op_sel_hi:[1,0]
	v_pk_mul_f32 v[18:19], v[12:13], s[44:45] op_sel_hi:[1,0]
	v_pk_mul_f32 v[12:13], v[6:7], s[44:45] op_sel_hi:[1,0]
	v_pk_mul_f32 v[14:15], v[4:5], s[44:45] op_sel_hi:[1,0]
	v_exp_f32_e32 v12, v12
	v_exp_f32_e32 v14, v14
	v_exp_f32_e32 v13, v13
	v_exp_f32_e32 v15, v15
	v_exp_f32_e32 v18, v18
	v_exp_f32_e32 v16, v16
	v_exp_f32_e32 v17, v17
	v_exp_f32_e32 v19, v19
	v_pk_add_f32 v[12:13], v[12:13], 1.0 op_sel_hi:[1,0]
	v_pk_add_f32 v[14:15], v[14:15], 1.0 op_sel_hi:[1,0]
	v_pk_add_f32 v[16:17], v[16:17], 1.0 op_sel_hi:[1,0]
	v_pk_add_f32 v[18:19], v[18:19], 1.0 op_sel_hi:[1,0]
	v_rcp_f32_e32 v14, v14
	v_rcp_f32_e32 v12, v12
	v_rcp_f32_e32 v13, v13
	v_rcp_f32_e32 v15, v15
	v_rcp_f32_e32 v18, v18
	v_rcp_f32_e32 v16, v16
	v_rcp_f32_e32 v17, v17
	v_rcp_f32_e32 v19, v19
	v_pk_mul_f32 v[2:3], v[2:3], v[128:129] op_sel_hi:[1,0]
	v_pk_mul_f32 v[0:1], v[0:1], v[128:129] op_sel_hi:[1,0]
	v_pk_mul_f32 v[2:3], v[6:7], v[2:3]
	v_pk_mul_f32 v[0:1], v[4:5], v[0:1]
	v_pk_mul_f32 v[4:5], v[2:3], v[12:13]
	v_pk_mul_f32 v[2:3], v[0:1], v[14:15]
	v_pk_mul_f32 v[10:11], v[10:11], v[16:17]
	v_pk_mul_f32 v[8:9], v[8:9], v[18:19]
	s_andn2_b64 vcc, exec, s[2:3]
	v_cvt_pk_bf16_f32 v0, v8, v9
	v_cvt_pk_bf16_f32 v1, v10, v11
	v_cvt_pk_bf16_f32 v2, v2, v3
	v_cvt_pk_bf16_f32 v3, v4, v5
	v_mad_i64_i32 v[4:5], s[4:5], v166, s35, v[112:113]
	v_lshl_add_u64 v[4:5], v[4:5], 0, v[114:115]
	s_mov_b32 s4, s16
	s_mov_b32 s5, s12
	s_mov_b64 s[6:7], s[18:19]
	global_store_dwordx4 v[4:5], v[0:3], off
	s_cbranch_vccnz .LBB0_1429
	s_waitcnt vmcnt(0)
	s_cmpk_gt_u32 s24, 0xff
	s_cbranch_scc1 .LBB0_1440
	s_barrier

	.amdhsa_kernel _Z4mega6Params
		.amdhsa_group_segment_fixed_size 0
		.amdhsa_private_segment_fixed_size 0
		.amdhsa_kernarg_size 512
		.amdhsa_user_sgpr_count 2
		.amdhsa_user_sgpr_dispatch_ptr 0
		.amdhsa_user_sgpr_queue_ptr 0
		.amdhsa_user_sgpr_kernarg_segment_ptr 1
		.amdhsa_user_sgpr_dispatch_id 0
		.amdhsa_user_sgpr_kernarg_preload_length 0
		.amdhsa_user_sgpr_kernarg_preload_offset 0
		.amdhsa_user_sgpr_private_segment_size 0
		.amdhsa_uses_dynamic_stack 0
		.amdhsa_enable_private_segment 0
		.amdhsa_system_sgpr_workgroup_id_x 1
		.amdhsa_system_sgpr_workgroup_id_y 0
		.amdhsa_system_sgpr_workgroup_id_z 0
		.amdhsa_system_sgpr_workgroup_info 0
		.amdhsa_system_vgpr_workitem_id 0
		.amdhsa_next_free_vgpr 255
		.amdhsa_next_free_sgpr 102
		.amdhsa_accum_offset 256
		.amdhsa_reserve_vcc 1
		.amdhsa_float_round_mode_32 0
		.amdhsa_float_round_mode_16_64 0
		.amdhsa_float_denorm_mode_32 3
		.amdhsa_float_denorm_mode_16_64 3
		.amdhsa_dx10_clamp 1
		.amdhsa_ieee_mode 1
		.amdhsa_fp16_overflow 0
		.amdhsa_tg_split 0
		.amdhsa_exception_fp_ieee_invalid_op 0
		.amdhsa_exception_fp_denorm_src 0
		.amdhsa_exception_fp_ieee_div_zero 0
		.amdhsa_exception_fp_ieee_overflow 0
		.amdhsa_exception_fp_ieee_underflow 0
		.amdhsa_exception_fp_ieee_inexact 0
		.amdhsa_exception_int_div_zero 0
	.end_amdhsa_kernel

amdhsa.kernels:
  - .agpr_count:     0
    .args:
      - .offset:         0
        .size:           256
        .value_kind:     by_value
      - .offset:         256
        .size:           4
        .value_kind:     hidden_block_count_x
      - .offset:         260
        .size:           4
        .value_kind:     hidden_block_count_y
      - .offset:         264
        .size:           4
        .value_kind:     hidden_block_count_z
      - .offset:         268
        .size:           2
        .value_kind:     hidden_group_size_x
      - .offset:         270
        .size:           2
        .value_kind:     hidden_group_size_y
      - .offset:         272
        .size:           2
        .value_kind:     hidden_group_size_z
      - .offset:         274
        .size:           2
        .value_kind:     hidden_remainder_x
      - .offset:         276
        .size:           2
        .value_kind:     hidden_remainder_y
      - .offset:         278
        .size:           2
        .value_kind:     hidden_remainder_z
      - .offset:         296
        .size:           8
        .value_kind:     hidden_global_offset_x
      - .offset:         304
        .size:           8
        .value_kind:     hidden_global_offset_y
      - .offset:         312
        .size:           8
        .value_kind:     hidden_global_offset_z
      - .offset:         320
        .size:           2
        .value_kind:     hidden_grid_dims
      - .offset:         376
        .size:           4
        .value_kind:     hidden_dynamic_lds_size
    .group_segment_fixed_size: 0
    .kernarg_segment_align: 8
    .kernarg_segment_size: 512
    .language:       OpenCL C
    .language_version:
      - 2
      - 0
    .max_flat_workgroup_size: 512
    .name:           _Z4mega6Params
    .private_segment_fixed_size: 0
    .sgpr_count:     108
    .sgpr_spill_count: 6
    .symbol:         _Z4mega6Params.kd
    .uniform_work_group_size: 1
    .uses_dynamic_stack: false
    .vgpr_count:     255
    .vgpr_spill_count: 0
    .wavefront_size: 64
